# att7 + snake MFMA order in all GEMM K-loops (one operand changes per MFMA; same per-accumulator order)
# speedup vs baseline: 1.0073x; 1.0073x over previous
.LBB0_217:
	ds_read_b128 v[154:157], v149
	ds_read_b128 v[158:161], v149 offset:1024
	ds_read_b128 v[162:165], v149 offset:2048
	ds_read_b128 v[166:169], v149 offset:3072
	ds_read_b128 v[170:173], v150
	ds_read_b128 v[174:177], v150 offset:1024
	ds_read_b128 v[178:181], v150 offset:2048
	ds_read_b128 v[182:185], v150 offset:3072
	s_add_u32 s0, s48, 0xfffc0080
	s_addc_u32 s1, s49, -1
	s_cmp_eq_u32 s62, 12
	s_cselect_b32 s55, s24, s1
	s_cselect_b32 s54, s25, s0
	s_cselect_b32 s1, s15, s57
	s_cselect_b32 s0, s31, s56
	v_lshl_add_u64 v[218:219], s[48:49], 0, v[136:137]
	s_add_i32 m0, s26, 0xc000
	ds_read_b128 v[186:189], v151
	ds_read_b128 v[190:193], v151 offset:1024
	ds_read_b128 v[194:197], v151 offset:2048
	ds_read_b128 v[198:201], v151 offset:3072
	ds_read_b128 v[202:205], v151 offset:4096
	ds_read_b128 v[206:209], v151 offset:5120
	ds_read_b128 v[210:213], v151 offset:6144
	ds_read_b128 v[214:217], v151 offset:7168
	global_load_lds_dwordx4 v[218:219], off
	v_lshl_add_u64 v[218:219], s[48:49], 0, v[138:139]
	s_add_i32 m0, s26, 0xe000
	s_nop 0
	global_load_lds_dwordx4 v[218:219], off
	s_waitcnt vmcnt(8)
	s_waitcnt lgkmcnt(0)
	s_barrier
	s_setprio 1
	s_waitcnt lgkmcnt(0)
	v_mfma_f32_16x16x32_bf16 v[124:127], v[154:157], v[186:189], v[124:127]
	v_mfma_f32_16x16x32_bf16 v[120:123], v[162:165], v[186:189], v[120:123]
	v_mfma_f32_16x16x32_bf16 v[104:107], v[162:165], v[194:197], v[104:107]
	v_mfma_f32_16x16x32_bf16 v[112:115], v[154:157], v[194:197], v[112:115]
	v_mfma_f32_16x16x32_bf16 v[96:99], v[154:157], v[202:205], v[96:99]
	v_mfma_f32_16x16x32_bf16 v[88:91], v[162:165], v[202:205], v[88:91]
	v_mfma_f32_16x16x32_bf16 v[72:75], v[162:165], v[210:213], v[72:75]
	v_mfma_f32_16x16x32_bf16 v[80:83], v[154:157], v[210:213], v[80:83]
	v_mfma_f32_16x16x32_bf16 v[124:127], v[158:161], v[190:193], v[124:127]
	v_mfma_f32_16x16x32_bf16 v[120:123], v[166:169], v[190:193], v[120:123]
	v_mfma_f32_16x16x32_bf16 v[104:107], v[166:169], v[198:201], v[104:107]
	v_mfma_f32_16x16x32_bf16 v[112:115], v[158:161], v[198:201], v[112:115]
	v_mfma_f32_16x16x32_bf16 v[96:99], v[158:161], v[206:209], v[96:99]
	v_mfma_f32_16x16x32_bf16 v[88:91], v[166:169], v[206:209], v[88:91]
	v_mfma_f32_16x16x32_bf16 v[72:75], v[166:169], v[214:217], v[72:75]
	v_mfma_f32_16x16x32_bf16 v[80:83], v[158:161], v[214:217], v[80:83]
	s_setprio 0
	s_setprio 1
	v_mfma_f32_16x16x32_bf16 v[116:119], v[170:173], v[186:189], v[116:119]
	v_mfma_f32_16x16x32_bf16 v[108:111], v[178:181], v[186:189], v[108:111]
	v_mfma_f32_16x16x32_bf16 v[92:95], v[178:181], v[194:197], v[92:95]
	v_mfma_f32_16x16x32_bf16 v[100:103], v[170:173], v[194:197], v[100:103]
	v_mfma_f32_16x16x32_bf16 v[84:87], v[170:173], v[202:205], v[84:87]
	v_mfma_f32_16x16x32_bf16 v[76:79], v[178:181], v[202:205], v[76:79]
	v_mfma_f32_16x16x32_bf16 v[64:67], v[178:181], v[210:213], v[64:67]
	v_mfma_f32_16x16x32_bf16 v[68:71], v[170:173], v[210:213], v[68:71]
	v_mfma_f32_16x16x32_bf16 v[116:119], v[174:177], v[190:193], v[116:119]
	v_mfma_f32_16x16x32_bf16 v[108:111], v[182:185], v[190:193], v[108:111]
	v_mfma_f32_16x16x32_bf16 v[92:95], v[182:185], v[198:201], v[92:95]
	v_mfma_f32_16x16x32_bf16 v[100:103], v[174:177], v[198:201], v[100:103]
	v_mfma_f32_16x16x32_bf16 v[84:87], v[174:177], v[206:209], v[84:87]
	v_mfma_f32_16x16x32_bf16 v[76:79], v[182:185], v[206:209], v[76:79]
	v_mfma_f32_16x16x32_bf16 v[64:67], v[182:185], v[214:217], v[64:67]
	v_mfma_f32_16x16x32_bf16 v[68:71], v[174:177], v[214:217], v[68:71]
	s_setprio 0
	s_barrier
	s_add_i32 s63, s47, s17
	v_lshl_add_u64 v[218:219], s[0:1], 0, v[132:133]
	s_mov_b32 m0, s63
	ds_read_b128 v[186:189], v151 offset:16384
	ds_read_b128 v[190:193], v151 offset:17408
	ds_read_b128 v[194:197], v151 offset:18432
	ds_read_b128 v[198:201], v151 offset:19456
	ds_read_b128 v[202:205], v151 offset:20480
	ds_read_b128 v[206:209], v151 offset:21504
	ds_read_b128 v[210:213], v151 offset:22528
	ds_read_b128 v[214:217], v151 offset:23552
	global_load_lds_dwordx4 v[218:219], off
	s_add_i32 m0, s63, 0x2000
	s_add_u32 s66, s0, 0x40000
	v_lshl_add_u64 v[220:221], s[0:1], 0, v[128:129]
	s_addc_u32 s67, s1, 0
	s_add_i32 s63, s50, s17
	global_load_lds_dwordx4 v[220:221], off
	v_lshl_add_u64 v[222:223], s[66:67], 0, v[132:133]
	s_mov_b32 m0, s63
	v_lshl_add_u64 v[224:225], s[54:55], 0, v[130:131]
	global_load_lds_dwordx4 v[222:223], off
	v_lshl_add_u64 v[222:223], s[66:67], 0, v[128:129]
	s_add_i32 m0, s63, 0x2000
	s_nop 0
	global_load_lds_dwordx4 v[222:223], off
	v_lshl_add_u64 v[222:223], s[54:55], 0, v[134:135]
	s_mov_b32 m0, s26
	s_nop 0
	global_load_lds_dwordx4 v[222:223], off
	s_mov_b32 m0, s27
	s_nop 0
	global_load_lds_dwordx4 v[224:225], off
	s_waitcnt vmcnt(8)
	s_waitcnt lgkmcnt(0)
	s_barrier
	s_setprio 1
	s_waitcnt lgkmcnt(0)
	v_mfma_f32_16x16x32_bf16 v[60:63], v[154:157], v[186:189], v[60:63]
	v_mfma_f32_16x16x32_bf16 v[56:59], v[162:165], v[186:189], v[56:59]
	v_mfma_f32_16x16x32_bf16 v[40:43], v[162:165], v[194:197], v[40:43]
	v_mfma_f32_16x16x32_bf16 v[48:51], v[154:157], v[194:197], v[48:51]
	v_mfma_f32_16x16x32_bf16 v[32:35], v[154:157], v[202:205], v[32:35]
	v_mfma_f32_16x16x32_bf16 v[24:27], v[162:165], v[202:205], v[24:27]
	v_mfma_f32_16x16x32_bf16 v[8:11], v[162:165], v[210:213], v[8:11]
	v_mfma_f32_16x16x32_bf16 v[16:19], v[154:157], v[210:213], v[16:19]
	v_mfma_f32_16x16x32_bf16 v[60:63], v[158:161], v[190:193], v[60:63]
	v_mfma_f32_16x16x32_bf16 v[56:59], v[166:169], v[190:193], v[56:59]
	v_mfma_f32_16x16x32_bf16 v[40:43], v[166:169], v[198:201], v[40:43]
	v_mfma_f32_16x16x32_bf16 v[48:51], v[158:161], v[198:201], v[48:51]
	v_mfma_f32_16x16x32_bf16 v[32:35], v[158:161], v[206:209], v[32:35]
	v_mfma_f32_16x16x32_bf16 v[24:27], v[166:169], v[206:209], v[24:27]
	v_mfma_f32_16x16x32_bf16 v[8:11], v[166:169], v[214:217], v[8:11]
	v_mfma_f32_16x16x32_bf16 v[16:19], v[158:161], v[214:217], v[16:19]
	s_setprio 0
	s_setprio 1
	v_mfma_f32_16x16x32_bf16 v[52:55], v[170:173], v[186:189], v[52:55]
	v_mfma_f32_16x16x32_bf16 v[44:47], v[178:181], v[186:189], v[44:47]
	v_mfma_f32_16x16x32_bf16 v[28:31], v[178:181], v[194:197], v[28:31]
	v_mfma_f32_16x16x32_bf16 v[36:39], v[170:173], v[194:197], v[36:39]
	v_mfma_f32_16x16x32_bf16 v[20:23], v[170:173], v[202:205], v[20:23]
	v_mfma_f32_16x16x32_bf16 v[12:15], v[178:181], v[202:205], v[12:15]
	v_mfma_f32_16x16x32_bf16 v[0:3], v[178:181], v[210:213], v[0:3]
	v_mfma_f32_16x16x32_bf16 v[4:7], v[170:173], v[210:213], v[4:7]
	v_mfma_f32_16x16x32_bf16 v[52:55], v[174:177], v[190:193], v[52:55]
	v_mfma_f32_16x16x32_bf16 v[44:47], v[182:185], v[190:193], v[44:47]
	v_mfma_f32_16x16x32_bf16 v[28:31], v[182:185], v[198:201], v[28:31]
	v_mfma_f32_16x16x32_bf16 v[36:39], v[174:177], v[198:201], v[36:39]
	v_mfma_f32_16x16x32_bf16 v[20:23], v[174:177], v[206:209], v[20:23]
	v_mfma_f32_16x16x32_bf16 v[12:15], v[182:185], v[206:209], v[12:15]
	v_mfma_f32_16x16x32_bf16 v[0:3], v[182:185], v[214:217], v[0:3]
	v_mfma_f32_16x16x32_bf16 v[4:7], v[174:177], v[214:217], v[4:7]
	s_setprio 0
	s_barrier
	s_add_i32 s63, 0, 0x18000
	v_add_u32_e32 v144, s63, v147
	s_add_i32 s66, 0, 0x1c000
	ds_read_b128 v[154:157], v144
	ds_read_b128 v[158:161], v144 offset:1024
	ds_read_b128 v[162:165], v144 offset:2048
	ds_read_b128 v[166:169], v144 offset:3072
	v_add_u32_e32 v144, s66, v147
	ds_read_b128 v[170:173], v144
	ds_read_b128 v[174:177], v144 offset:1024
	ds_read_b128 v[178:181], v144 offset:2048
	ds_read_b128 v[182:185], v144 offset:3072
	s_add_u32 s54, s54, 0x40000
	s_addc_u32 s55, s55, 0
	s_mov_b32 m0, s33
	v_lshl_add_u64 v[226:227], s[54:55], 0, v[134:135]
	ds_read_b128 v[186:189], v151 offset:32768
	ds_read_b128 v[190:193], v151 offset:33792
	ds_read_b128 v[194:197], v151 offset:34816
	ds_read_b128 v[198:201], v151 offset:35840
	ds_read_b128 v[202:205], v151 offset:36864
	ds_read_b128 v[206:209], v151 offset:37888
	ds_read_b128 v[210:213], v151 offset:38912
	ds_read_b128 v[214:217], v151 offset:39936
	global_load_lds_dwordx4 v[226:227], off
	v_lshl_add_u64 v[226:227], s[54:55], 0, v[130:131]
	s_mov_b32 m0, s34
	s_nop 0
	global_load_lds_dwordx4 v[226:227], off
	s_waitcnt vmcnt(8)
	s_waitcnt lgkmcnt(0)
	s_barrier
	s_setprio 1
	s_waitcnt lgkmcnt(0)
	v_mfma_f32_16x16x32_bf16 v[124:127], v[154:157], v[186:189], v[124:127]
	v_mfma_f32_16x16x32_bf16 v[120:123], v[162:165], v[186:189], v[120:123]
	v_mfma_f32_16x16x32_bf16 v[104:107], v[162:165], v[194:197], v[104:107]
	v_mfma_f32_16x16x32_bf16 v[112:115], v[154:157], v[194:197], v[112:115]
	v_mfma_f32_16x16x32_bf16 v[96:99], v[154:157], v[202:205], v[96:99]
	v_mfma_f32_16x16x32_bf16 v[88:91], v[162:165], v[202:205], v[88:91]
	v_mfma_f32_16x16x32_bf16 v[72:75], v[162:165], v[210:213], v[72:75]
	v_mfma_f32_16x16x32_bf16 v[80:83], v[154:157], v[210:213], v[80:83]
	v_mfma_f32_16x16x32_bf16 v[124:127], v[158:161], v[190:193], v[124:127]
	v_mfma_f32_16x16x32_bf16 v[120:123], v[166:169], v[190:193], v[120:123]
	v_mfma_f32_16x16x32_bf16 v[104:107], v[166:169], v[198:201], v[104:107]
	v_mfma_f32_16x16x32_bf16 v[112:115], v[158:161], v[198:201], v[112:115]
	v_mfma_f32_16x16x32_bf16 v[96:99], v[158:161], v[206:209], v[96:99]
	v_mfma_f32_16x16x32_bf16 v[88:91], v[166:169], v[206:209], v[88:91]
	v_mfma_f32_16x16x32_bf16 v[72:75], v[166:169], v[214:217], v[72:75]
	v_mfma_f32_16x16x32_bf16 v[80:83], v[158:161], v[214:217], v[80:83]
	s_setprio 0
	s_setprio 1
	v_mfma_f32_16x16x32_bf16 v[116:119], v[170:173], v[186:189], v[116:119]
	v_mfma_f32_16x16x32_bf16 v[108:111], v[178:181], v[186:189], v[108:111]
	v_mfma_f32_16x16x32_bf16 v[92:95], v[178:181], v[194:197], v[92:95]
	v_mfma_f32_16x16x32_bf16 v[100:103], v[170:173], v[194:197], v[100:103]
	v_mfma_f32_16x16x32_bf16 v[84:87], v[170:173], v[202:205], v[84:87]
	v_mfma_f32_16x16x32_bf16 v[76:79], v[178:181], v[202:205], v[76:79]
	v_mfma_f32_16x16x32_bf16 v[64:67], v[178:181], v[210:213], v[64:67]
	v_mfma_f32_16x16x32_bf16 v[68:71], v[170:173], v[210:213], v[68:71]
	v_mfma_f32_16x16x32_bf16 v[116:119], v[174:177], v[190:193], v[116:119]
	v_mfma_f32_16x16x32_bf16 v[108:111], v[182:185], v[190:193], v[108:111]
	v_mfma_f32_16x16x32_bf16 v[92:95], v[182:185], v[198:201], v[92:95]
	v_mfma_f32_16x16x32_bf16 v[100:103], v[174:177], v[198:201], v[100:103]
	v_mfma_f32_16x16x32_bf16 v[84:87], v[174:177], v[206:209], v[84:87]
	v_mfma_f32_16x16x32_bf16 v[76:79], v[182:185], v[206:209], v[76:79]
	v_mfma_f32_16x16x32_bf16 v[64:67], v[182:185], v[214:217], v[64:67]
	v_mfma_f32_16x16x32_bf16 v[68:71], v[174:177], v[214:217], v[68:71]
	s_setprio 0
	s_barrier
	s_add_i32 s54, s63, s17
	v_lshl_add_u64 v[218:219], v[218:219], 0, s[10:11]
	s_mov_b32 m0, s54
	ds_read_b128 v[186:189], v151 offset:49152
	ds_read_b128 v[190:193], v151 offset:50176
	ds_read_b128 v[194:197], v151 offset:51200
	ds_read_b128 v[198:201], v151 offset:52224
	ds_read_b128 v[202:205], v151 offset:53248
	ds_read_b128 v[206:209], v151 offset:54272
	ds_read_b128 v[210:213], v151 offset:55296
	ds_read_b128 v[214:217], v151 offset:56320
	global_load_lds_dwordx4 v[218:219], off
	s_add_i32 m0, s54, 0x2000
	s_add_u32 s0, s0, 0x40080
	v_lshl_add_u64 v[218:219], v[220:221], 0, s[10:11]
	s_addc_u32 s1, s1, 0
	s_add_i32 s54, s66, s17
	global_load_lds_dwordx4 v[218:219], off
	v_lshl_add_u64 v[218:219], s[0:1], 0, v[132:133]
	s_mov_b32 m0, s54
	s_nop 0
	global_load_lds_dwordx4 v[218:219], off
	v_lshl_add_u64 v[218:219], s[0:1], 0, v[128:129]
	s_add_i32 m0, s54, 0x2000
	s_nop 0
	global_load_lds_dwordx4 v[218:219], off
	v_lshl_add_u64 v[218:219], v[222:223], 0, s[10:11]
	s_mov_b32 m0, s43
	s_nop 0
	global_load_lds_dwordx4 v[218:219], off
	v_lshl_add_u64 v[218:219], v[224:225], 0, s[10:11]
	s_mov_b32 m0, s44
	s_nop 0
	global_load_lds_dwordx4 v[218:219], off
	s_waitcnt vmcnt(8)
	s_waitcnt lgkmcnt(0)
	s_barrier
	s_setprio 1
	s_waitcnt lgkmcnt(0)
	v_mfma_f32_16x16x32_bf16 v[60:63], v[154:157], v[186:189], v[60:63]
	v_mfma_f32_16x16x32_bf16 v[56:59], v[162:165], v[186:189], v[56:59]
	v_mfma_f32_16x16x32_bf16 v[40:43], v[162:165], v[194:197], v[40:43]
	v_mfma_f32_16x16x32_bf16 v[48:51], v[154:157], v[194:197], v[48:51]
	v_mfma_f32_16x16x32_bf16 v[32:35], v[154:157], v[202:205], v[32:35]
	v_mfma_f32_16x16x32_bf16 v[24:27], v[162:165], v[202:205], v[24:27]
	v_mfma_f32_16x16x32_bf16 v[8:11], v[162:165], v[210:213], v[8:11]
	v_mfma_f32_16x16x32_bf16 v[16:19], v[154:157], v[210:213], v[16:19]
	v_mfma_f32_16x16x32_bf16 v[60:63], v[158:161], v[190:193], v[60:63]
	v_mfma_f32_16x16x32_bf16 v[56:59], v[166:169], v[190:193], v[56:59]
	v_mfma_f32_16x16x32_bf16 v[40:43], v[166:169], v[198:201], v[40:43]
	v_mfma_f32_16x16x32_bf16 v[48:51], v[158:161], v[198:201], v[48:51]
	v_mfma_f32_16x16x32_bf16 v[32:35], v[158:161], v[206:209], v[32:35]
	v_mfma_f32_16x16x32_bf16 v[24:27], v[166:169], v[206:209], v[24:27]
	v_mfma_f32_16x16x32_bf16 v[8:11], v[166:169], v[214:217], v[8:11]
	v_mfma_f32_16x16x32_bf16 v[16:19], v[158:161], v[214:217], v[16:19]
	s_setprio 0
	s_setprio 1
	v_mfma_f32_16x16x32_bf16 v[52:55], v[170:173], v[186:189], v[52:55]
	v_mfma_f32_16x16x32_bf16 v[44:47], v[178:181], v[186:189], v[44:47]
	v_mfma_f32_16x16x32_bf16 v[28:31], v[178:181], v[194:197], v[28:31]
	v_mfma_f32_16x16x32_bf16 v[36:39], v[170:173], v[194:197], v[36:39]
	v_mfma_f32_16x16x32_bf16 v[20:23], v[170:173], v[202:205], v[20:23]
	v_mfma_f32_16x16x32_bf16 v[12:15], v[178:181], v[202:205], v[12:15]
	v_mfma_f32_16x16x32_bf16 v[0:3], v[178:181], v[210:213], v[0:3]
	v_mfma_f32_16x16x32_bf16 v[4:7], v[170:173], v[210:213], v[4:7]
	v_mfma_f32_16x16x32_bf16 v[52:55], v[174:177], v[190:193], v[52:55]
	v_mfma_f32_16x16x32_bf16 v[44:47], v[182:185], v[190:193], v[44:47]
	v_mfma_f32_16x16x32_bf16 v[28:31], v[182:185], v[198:201], v[28:31]
	v_mfma_f32_16x16x32_bf16 v[36:39], v[174:177], v[198:201], v[36:39]
	v_mfma_f32_16x16x32_bf16 v[20:23], v[174:177], v[206:209], v[20:23]
	v_mfma_f32_16x16x32_bf16 v[12:15], v[182:185], v[206:209], v[12:15]
	v_mfma_f32_16x16x32_bf16 v[0:3], v[182:185], v[214:217], v[0:3]
	v_mfma_f32_16x16x32_bf16 v[4:7], v[174:177], v[214:217], v[4:7]
	s_setprio 0
	s_barrier
	s_add_i32 s62, s62, 2
	s_add_u32 s48, s48, 0x100
	s_addc_u32 s49, s49, 0
	s_add_u32 s56, s56, 0x100
	s_addc_u32 s57, s57, 0
	s_cmp_gt_u32 s62, 13
	s_cbranch_scc0 .LBB0_217
	s_and_b64 vcc, exec, s[12:13]
	s_cbranch_vccz .LBB0_220
	s_barrier

.LBB0_533:
	v_add_u32_e32 v1, s34, v225
	ds_read_b128 v[132:135], v1
	ds_read_b128 v[136:139], v1 offset:1024
	ds_read_b128 v[140:143], v1 offset:2048
	ds_read_b128 v[144:147], v1 offset:3072
	v_add_u32_e32 v1, s35, v225
	ds_read_b128 v[148:151], v1
	ds_read_b128 v[152:155], v1 offset:1024
	ds_read_b128 v[156:159], v1 offset:2048
	ds_read_b128 v[160:163], v1 offset:3072
	s_add_u32 s0, s68, 0xfffc0080
	s_addc_u32 s1, s69, -1
	s_cmp_eq_u32 s50, 12
	s_cselect_b32 s71, s19, s1
	s_cselect_b32 s70, s38, s0
	s_cselect_b32 s1, s39, s47
	s_cselect_b32 s0, s45, s46
	v_lshl_add_u64 v[2:3], s[68:69], 0, v[196:197]
	s_add_i32 m0, s25, 0xc000
	ds_read_b128 v[164:167], v227
	ds_read_b128 v[168:171], v227 offset:1024
	ds_read_b128 v[172:175], v227 offset:2048
	ds_read_b128 v[176:179], v227 offset:3072
	ds_read_b128 v[180:183], v227 offset:4096
	ds_read_b128 v[184:187], v227 offset:5120
	ds_read_b128 v[204:207], v227 offset:6144
	ds_read_b128 v[208:211], v227 offset:7168
	global_load_lds_dwordx4 v[2:3], off
	v_lshl_add_u64 v[2:3], s[68:69], 0, v[198:199]
	s_add_i32 m0, s25, 0xe000
	s_nop 0
	global_load_lds_dwordx4 v[2:3], off
	s_waitcnt vmcnt(8)
	s_waitcnt lgkmcnt(0)
	s_barrier
	s_setprio 1
	s_waitcnt lgkmcnt(0)
	v_mfma_f32_16x16x32_bf16 v[128:131], v[132:135], v[164:167], v[128:131]
	v_mfma_f32_16x16x32_bf16 v[124:127], v[140:143], v[164:167], v[124:127]
	v_mfma_f32_16x16x32_bf16 v[116:119], v[140:143], v[172:175], v[116:119]
	v_mfma_f32_16x16x32_bf16 v[120:123], v[132:135], v[172:175], v[120:123]
	v_mfma_f32_16x16x32_bf16 v[112:115], v[132:135], v[180:183], v[112:115]
	v_mfma_f32_16x16x32_bf16 v[108:111], v[140:143], v[180:183], v[108:111]
	v_mfma_f32_16x16x32_bf16 v[100:103], v[140:143], v[204:207], v[100:103]
	v_mfma_f32_16x16x32_bf16 v[104:107], v[132:135], v[204:207], v[104:107]
	v_mfma_f32_16x16x32_bf16 v[128:131], v[136:139], v[168:171], v[128:131]
	v_mfma_f32_16x16x32_bf16 v[124:127], v[144:147], v[168:171], v[124:127]
	v_mfma_f32_16x16x32_bf16 v[116:119], v[144:147], v[176:179], v[116:119]
	v_mfma_f32_16x16x32_bf16 v[120:123], v[136:139], v[176:179], v[120:123]
	v_mfma_f32_16x16x32_bf16 v[112:115], v[136:139], v[184:187], v[112:115]
	v_mfma_f32_16x16x32_bf16 v[108:111], v[144:147], v[184:187], v[108:111]
	v_mfma_f32_16x16x32_bf16 v[100:103], v[144:147], v[208:211], v[100:103]
	v_mfma_f32_16x16x32_bf16 v[104:107], v[136:139], v[208:211], v[104:107]
	s_setprio 0
	s_setprio 1
	v_mfma_f32_16x16x32_bf16 v[96:99], v[148:151], v[164:167], v[96:99]
	v_mfma_f32_16x16x32_bf16 v[92:95], v[156:159], v[164:167], v[92:95]
	v_mfma_f32_16x16x32_bf16 v[84:87], v[156:159], v[172:175], v[84:87]
	v_mfma_f32_16x16x32_bf16 v[88:91], v[148:151], v[172:175], v[88:91]
	v_mfma_f32_16x16x32_bf16 v[80:83], v[148:151], v[180:183], v[80:83]
	v_mfma_f32_16x16x32_bf16 v[76:79], v[156:159], v[180:183], v[76:79]
	v_mfma_f32_16x16x32_bf16 v[68:71], v[156:159], v[204:207], v[68:71]
	v_mfma_f32_16x16x32_bf16 v[72:75], v[148:151], v[204:207], v[72:75]
	v_mfma_f32_16x16x32_bf16 v[96:99], v[152:155], v[168:171], v[96:99]
	v_mfma_f32_16x16x32_bf16 v[92:95], v[160:163], v[168:171], v[92:95]
	v_mfma_f32_16x16x32_bf16 v[84:87], v[160:163], v[176:179], v[84:87]
	v_mfma_f32_16x16x32_bf16 v[88:91], v[152:155], v[176:179], v[88:91]
	v_mfma_f32_16x16x32_bf16 v[80:83], v[152:155], v[184:187], v[80:83]
	v_mfma_f32_16x16x32_bf16 v[76:79], v[160:163], v[184:187], v[76:79]
	v_mfma_f32_16x16x32_bf16 v[68:71], v[160:163], v[208:211], v[68:71]
	v_mfma_f32_16x16x32_bf16 v[72:75], v[152:155], v[208:211], v[72:75]
	s_setprio 0
	s_barrier
	s_add_i32 s51, s34, s24
	v_lshl_add_u64 v[212:213], s[0:1], 0, v[190:191]
	s_mov_b32 m0, s51
	ds_read_b128 v[164:167], v227 offset:16384
	ds_read_b128 v[168:171], v227 offset:17408
	ds_read_b128 v[172:175], v227 offset:18432
	ds_read_b128 v[176:179], v227 offset:19456
	ds_read_b128 v[180:183], v227 offset:20480
	ds_read_b128 v[184:187], v227 offset:21504
	ds_read_b128 v[204:207], v227 offset:22528
	ds_read_b128 v[208:211], v227 offset:23552
	global_load_lds_dwordx4 v[212:213], off
	s_add_i32 m0, s51, 0x2000
	s_add_u32 s72, s0, 0x40000
	v_lshl_add_u64 v[214:215], s[0:1], 0, v[194:195]
	s_addc_u32 s73, s1, 0
	s_add_i32 s51, s35, s24
	global_load_lds_dwordx4 v[214:215], off
	v_lshl_add_u64 v[2:3], s[72:73], 0, v[190:191]
	s_mov_b32 m0, s51
	v_lshl_add_u64 v[216:217], s[70:71], 0, v[188:189]
	global_load_lds_dwordx4 v[2:3], off
	v_lshl_add_u64 v[2:3], s[72:73], 0, v[194:195]
	s_add_i32 m0, s51, 0x2000
	v_lshl_add_u64 v[218:219], s[70:71], 0, v[192:193]
	global_load_lds_dwordx4 v[2:3], off
	s_mov_b32 m0, s25
	s_nop 0
	global_load_lds_dwordx4 v[216:217], off
	s_mov_b32 m0, s26
	s_nop 0
	global_load_lds_dwordx4 v[218:219], off
	s_waitcnt vmcnt(8)
	s_waitcnt lgkmcnt(0)
	s_barrier
	s_setprio 1
	s_waitcnt lgkmcnt(0)
	v_mfma_f32_16x16x32_bf16 v[64:67], v[132:135], v[164:167], v[64:67]
	v_mfma_f32_16x16x32_bf16 v[60:63], v[140:143], v[164:167], v[60:63]
	v_mfma_f32_16x16x32_bf16 v[52:55], v[140:143], v[172:175], v[52:55]
	v_mfma_f32_16x16x32_bf16 v[56:59], v[132:135], v[172:175], v[56:59]
	v_mfma_f32_16x16x32_bf16 v[48:51], v[132:135], v[180:183], v[48:51]
	v_mfma_f32_16x16x32_bf16 v[44:47], v[140:143], v[180:183], v[44:47]
	v_mfma_f32_16x16x32_bf16 v[36:39], v[140:143], v[204:207], v[36:39]
	v_mfma_f32_16x16x32_bf16 v[40:43], v[132:135], v[204:207], v[40:43]
	v_mfma_f32_16x16x32_bf16 v[64:67], v[136:139], v[168:171], v[64:67]
	v_mfma_f32_16x16x32_bf16 v[60:63], v[144:147], v[168:171], v[60:63]
	v_mfma_f32_16x16x32_bf16 v[52:55], v[144:147], v[176:179], v[52:55]
	v_mfma_f32_16x16x32_bf16 v[56:59], v[136:139], v[176:179], v[56:59]
	v_mfma_f32_16x16x32_bf16 v[48:51], v[136:139], v[184:187], v[48:51]
	v_mfma_f32_16x16x32_bf16 v[44:47], v[144:147], v[184:187], v[44:47]
	v_mfma_f32_16x16x32_bf16 v[36:39], v[144:147], v[208:211], v[36:39]
	v_mfma_f32_16x16x32_bf16 v[40:43], v[136:139], v[208:211], v[40:43]
	s_setprio 0
	s_setprio 1
	v_mfma_f32_16x16x32_bf16 v[32:35], v[148:151], v[164:167], v[32:35]
	v_mfma_f32_16x16x32_bf16 v[28:31], v[156:159], v[164:167], v[28:31]
	v_mfma_f32_16x16x32_bf16 v[20:23], v[156:159], v[172:175], v[20:23]
	v_mfma_f32_16x16x32_bf16 v[24:27], v[148:151], v[172:175], v[24:27]
	v_mfma_f32_16x16x32_bf16 v[16:19], v[148:151], v[180:183], v[16:19]
	v_mfma_f32_16x16x32_bf16 v[12:15], v[156:159], v[180:183], v[12:15]
	v_mfma_f32_16x16x32_bf16 v[2:5], v[156:159], v[204:207], v[4:7]
	v_mfma_f32_16x16x32_bf16 v[8:11], v[148:151], v[204:207], v[8:11]
	v_mfma_f32_16x16x32_bf16 v[32:35], v[152:155], v[168:171], v[32:35]
	v_mfma_f32_16x16x32_bf16 v[28:31], v[160:163], v[168:171], v[28:31]
	v_mfma_f32_16x16x32_bf16 v[20:23], v[160:163], v[176:179], v[20:23]
	v_mfma_f32_16x16x32_bf16 v[24:27], v[152:155], v[176:179], v[24:27]
	v_mfma_f32_16x16x32_bf16 v[16:19], v[152:155], v[184:187], v[16:19]
	v_mfma_f32_16x16x32_bf16 v[12:15], v[160:163], v[184:187], v[12:15]
	v_mfma_f32_16x16x32_bf16 v[2:5], v[160:163], v[208:211], v[2:5]
	v_mfma_f32_16x16x32_bf16 v[8:11], v[152:155], v[208:211], v[8:11]
	s_setprio 0
	s_barrier
	s_add_i32 s51, 0, 0x18000
	v_add_u32_e32 v1, s51, v225
	s_add_i32 s57, 0, 0x1c000
	ds_read_b128 v[132:135], v1
	ds_read_b128 v[136:139], v1 offset:1024
	ds_read_b128 v[140:143], v1 offset:2048
	ds_read_b128 v[144:147], v1 offset:3072
	v_add_u32_e32 v1, s57, v225
	ds_read_b128 v[148:151], v1
	ds_read_b128 v[152:155], v1 offset:1024
	ds_read_b128 v[156:159], v1 offset:2048
	ds_read_b128 v[160:163], v1 offset:3072
	s_add_u32 s70, s70, 0x40000
	s_addc_u32 s71, s71, 0
	s_mov_b32 m0, s27
	v_lshl_add_u64 v[6:7], s[70:71], 0, v[188:189]
	ds_read_b128 v[164:167], v227 offset:32768
	ds_read_b128 v[168:171], v227 offset:33792
	ds_read_b128 v[172:175], v227 offset:34816
	ds_read_b128 v[176:179], v227 offset:35840
	ds_read_b128 v[180:183], v227 offset:36864
	ds_read_b128 v[184:187], v227 offset:37888
	ds_read_b128 v[204:207], v227 offset:38912
	ds_read_b128 v[208:211], v227 offset:39936
	global_load_lds_dwordx4 v[6:7], off
	v_lshl_add_u64 v[6:7], s[70:71], 0, v[192:193]
	s_mov_b32 m0, s30
	s_nop 0
	global_load_lds_dwordx4 v[6:7], off
	s_waitcnt vmcnt(8)
	s_waitcnt lgkmcnt(0)
	s_barrier
	s_setprio 1
	s_waitcnt lgkmcnt(0)
	v_mfma_f32_16x16x32_bf16 v[128:131], v[132:135], v[164:167], v[128:131]
	v_mfma_f32_16x16x32_bf16 v[124:127], v[140:143], v[164:167], v[124:127]
	v_mfma_f32_16x16x32_bf16 v[116:119], v[140:143], v[172:175], v[116:119]
	v_mfma_f32_16x16x32_bf16 v[120:123], v[132:135], v[172:175], v[120:123]
	v_mfma_f32_16x16x32_bf16 v[112:115], v[132:135], v[180:183], v[112:115]
	v_mfma_f32_16x16x32_bf16 v[108:111], v[140:143], v[180:183], v[108:111]
	v_mfma_f32_16x16x32_bf16 v[100:103], v[140:143], v[204:207], v[100:103]
	v_mfma_f32_16x16x32_bf16 v[104:107], v[132:135], v[204:207], v[104:107]
	v_mfma_f32_16x16x32_bf16 v[128:131], v[136:139], v[168:171], v[128:131]
	v_mfma_f32_16x16x32_bf16 v[124:127], v[144:147], v[168:171], v[124:127]
	v_mfma_f32_16x16x32_bf16 v[116:119], v[144:147], v[176:179], v[116:119]
	v_mfma_f32_16x16x32_bf16 v[120:123], v[136:139], v[176:179], v[120:123]
	v_mfma_f32_16x16x32_bf16 v[112:115], v[136:139], v[184:187], v[112:115]
	v_mfma_f32_16x16x32_bf16 v[108:111], v[144:147], v[184:187], v[108:111]
	v_mfma_f32_16x16x32_bf16 v[100:103], v[144:147], v[208:211], v[100:103]
	v_mfma_f32_16x16x32_bf16 v[104:107], v[136:139], v[208:211], v[104:107]
	s_setprio 0
	s_setprio 1
	v_mfma_f32_16x16x32_bf16 v[96:99], v[148:151], v[164:167], v[96:99]
	v_mfma_f32_16x16x32_bf16 v[92:95], v[156:159], v[164:167], v[92:95]
	v_mfma_f32_16x16x32_bf16 v[84:87], v[156:159], v[172:175], v[84:87]
	v_mfma_f32_16x16x32_bf16 v[88:91], v[148:151], v[172:175], v[88:91]
	v_mfma_f32_16x16x32_bf16 v[80:83], v[148:151], v[180:183], v[80:83]
	v_mfma_f32_16x16x32_bf16 v[76:79], v[156:159], v[180:183], v[76:79]
	v_mfma_f32_16x16x32_bf16 v[68:71], v[156:159], v[204:207], v[68:71]
	v_mfma_f32_16x16x32_bf16 v[72:75], v[148:151], v[204:207], v[72:75]
	v_mfma_f32_16x16x32_bf16 v[96:99], v[152:155], v[168:171], v[96:99]
	v_mfma_f32_16x16x32_bf16 v[92:95], v[160:163], v[168:171], v[92:95]
	v_mfma_f32_16x16x32_bf16 v[84:87], v[160:163], v[176:179], v[84:87]
	v_mfma_f32_16x16x32_bf16 v[88:91], v[152:155], v[176:179], v[88:91]
	v_mfma_f32_16x16x32_bf16 v[80:83], v[152:155], v[184:187], v[80:83]
	v_mfma_f32_16x16x32_bf16 v[76:79], v[160:163], v[184:187], v[76:79]
	v_mfma_f32_16x16x32_bf16 v[68:71], v[160:163], v[208:211], v[68:71]
	v_mfma_f32_16x16x32_bf16 v[72:75], v[152:155], v[208:211], v[72:75]
	s_setprio 0
	s_barrier
	s_add_i32 s51, s51, s24
	v_lshl_add_u64 v[6:7], v[212:213], 0, s[14:15]
	s_mov_b32 m0, s51
	ds_read_b128 v[164:167], v227 offset:49152
	ds_read_b128 v[168:171], v227 offset:50176
	ds_read_b128 v[172:175], v227 offset:51200
	ds_read_b128 v[176:179], v227 offset:52224
	ds_read_b128 v[180:183], v227 offset:53248
	ds_read_b128 v[184:187], v227 offset:54272
	ds_read_b128 v[204:207], v227 offset:55296
	ds_read_b128 v[208:211], v227 offset:56320
	global_load_lds_dwordx4 v[6:7], off
	s_add_i32 m0, s51, 0x2000
	s_add_u32 s0, s0, 0x40080
	v_lshl_add_u64 v[6:7], v[214:215], 0, s[14:15]
	s_addc_u32 s1, s1, 0
	s_add_i32 s51, s57, s24
	global_load_lds_dwordx4 v[6:7], off
	v_lshl_add_u64 v[6:7], s[0:1], 0, v[190:191]
	s_mov_b32 m0, s51
	s_nop 0
	global_load_lds_dwordx4 v[6:7], off
	v_lshl_add_u64 v[6:7], s[0:1], 0, v[194:195]
	s_add_i32 m0, s51, 0x2000
	s_nop 0
	global_load_lds_dwordx4 v[6:7], off
	v_lshl_add_u64 v[6:7], v[216:217], 0, s[14:15]
	s_mov_b32 m0, s31
	s_nop 0
	global_load_lds_dwordx4 v[6:7], off
	v_lshl_add_u64 v[6:7], v[218:219], 0, s[14:15]
	s_mov_b32 m0, s33
	s_nop 0
	global_load_lds_dwordx4 v[6:7], off
	s_waitcnt vmcnt(8)
	s_waitcnt lgkmcnt(0)
	s_barrier
	s_setprio 1
	s_waitcnt lgkmcnt(0)
	v_mfma_f32_16x16x32_bf16 v[64:67], v[132:135], v[164:167], v[64:67]
	v_mfma_f32_16x16x32_bf16 v[60:63], v[140:143], v[164:167], v[60:63]
	v_mfma_f32_16x16x32_bf16 v[52:55], v[140:143], v[172:175], v[52:55]
	v_mfma_f32_16x16x32_bf16 v[56:59], v[132:135], v[172:175], v[56:59]
	v_mfma_f32_16x16x32_bf16 v[48:51], v[132:135], v[180:183], v[48:51]
	v_mfma_f32_16x16x32_bf16 v[44:47], v[140:143], v[180:183], v[44:47]
	v_mfma_f32_16x16x32_bf16 v[36:39], v[140:143], v[204:207], v[36:39]
	v_mfma_f32_16x16x32_bf16 v[40:43], v[132:135], v[204:207], v[40:43]
	v_mfma_f32_16x16x32_bf16 v[64:67], v[136:139], v[168:171], v[64:67]
	v_mfma_f32_16x16x32_bf16 v[60:63], v[144:147], v[168:171], v[60:63]
	v_mfma_f32_16x16x32_bf16 v[52:55], v[144:147], v[176:179], v[52:55]
	v_mfma_f32_16x16x32_bf16 v[56:59], v[136:139], v[176:179], v[56:59]
	v_mfma_f32_16x16x32_bf16 v[48:51], v[136:139], v[184:187], v[48:51]
	v_mfma_f32_16x16x32_bf16 v[44:47], v[144:147], v[184:187], v[44:47]
	v_mfma_f32_16x16x32_bf16 v[36:39], v[144:147], v[208:211], v[36:39]
	v_mfma_f32_16x16x32_bf16 v[40:43], v[136:139], v[208:211], v[40:43]
	s_setprio 0
	s_setprio 1
	v_mfma_f32_16x16x32_bf16 v[32:35], v[148:151], v[164:167], v[32:35]
	v_mfma_f32_16x16x32_bf16 v[28:31], v[156:159], v[164:167], v[28:31]
	v_mfma_f32_16x16x32_bf16 v[20:23], v[156:159], v[172:175], v[20:23]
	v_mfma_f32_16x16x32_bf16 v[24:27], v[148:151], v[172:175], v[24:27]
	v_mfma_f32_16x16x32_bf16 v[16:19], v[148:151], v[180:183], v[16:19]
	v_mfma_f32_16x16x32_bf16 v[12:15], v[156:159], v[180:183], v[12:15]
	v_mfma_f32_16x16x32_bf16 v[2:5], v[156:159], v[204:207], v[2:5]
	v_mfma_f32_16x16x32_bf16 v[6:9], v[148:151], v[204:207], v[8:11]
	v_mfma_f32_16x16x32_bf16 v[32:35], v[152:155], v[168:171], v[32:35]
	v_mfma_f32_16x16x32_bf16 v[28:31], v[160:163], v[168:171], v[28:31]
	v_mfma_f32_16x16x32_bf16 v[20:23], v[160:163], v[176:179], v[20:23]
	v_mfma_f32_16x16x32_bf16 v[24:27], v[152:155], v[176:179], v[24:27]
	v_mfma_f32_16x16x32_bf16 v[16:19], v[152:155], v[184:187], v[16:19]
	v_mfma_f32_16x16x32_bf16 v[12:15], v[160:163], v[184:187], v[12:15]
	v_mfma_f32_16x16x32_bf16 v[4:7], v[160:163], v[208:211], v[2:5]
	v_mfma_f32_16x16x32_bf16 v[8:11], v[152:155], v[208:211], v[6:9]
	s_setprio 0
	s_barrier
	s_add_i32 s50, s50, 2
	s_add_u32 s68, s68, 0x100
	s_addc_u32 s69, s69, 0
	s_add_u32 s46, s46, 0x100
	s_addc_u32 s47, s47, 0
	s_cmp_gt_u32 s50, 13
	s_cbranch_scc0 .LBB0_533
	s_and_b64 vcc, exec, s[40:41]
	s_cbranch_vccz .LBB0_536
	s_barrier

.LBB0_617:
	ds_read_b128 v[128:131], v209
	ds_read_b128 v[132:135], v209 offset:1024
	ds_read_b128 v[136:139], v209 offset:2048
	ds_read_b128 v[140:143], v209 offset:3072
	ds_read_b128 v[144:147], v210
	ds_read_b128 v[148:151], v210 offset:1024
	ds_read_b128 v[152:155], v210 offset:2048
	ds_read_b128 v[156:159], v210 offset:3072
	s_add_u32 s0, s62, 0xfffc0080
	s_addc_u32 s1, s63, -1
	s_cmp_eq_u32 s49, 12
	s_cselect_b32 s65, s38, s1
	s_cselect_b32 s64, s39, s0
	s_cselect_b32 s1, s43, s47
	s_cselect_b32 s0, s45, s46
	v_lshl_add_u64 v[204:205], s[62:63], 0, v[184:185]
	s_add_i32 m0, s18, 0xc000
	ds_read_b128 v[160:163], v211
	ds_read_b128 v[164:167], v211 offset:1024
	ds_read_b128 v[168:171], v211 offset:2048
	ds_read_b128 v[172:175], v211 offset:3072
	ds_read_b128 v[192:195], v211 offset:4096
	ds_read_b128 v[196:199], v211 offset:5120
	ds_read_b128 v[200:203], v211 offset:6144
	ds_read_b128 v[212:215], v211 offset:7168
	global_load_lds_dwordx4 v[204:205], off
	v_lshl_add_u64 v[204:205], s[62:63], 0, v[186:187]
	s_add_i32 m0, s18, 0xe000
	s_nop 0
	global_load_lds_dwordx4 v[204:205], off
	s_waitcnt vmcnt(8)
	s_waitcnt lgkmcnt(0)
	s_barrier
	s_setprio 1
	s_waitcnt lgkmcnt(0)
	v_mfma_f32_16x16x32_bf16 v[124:127], v[128:131], v[160:163], v[124:127]
	v_mfma_f32_16x16x32_bf16 v[120:123], v[136:139], v[160:163], v[120:123]
	v_mfma_f32_16x16x32_bf16 v[104:107], v[136:139], v[168:171], v[104:107]
	v_mfma_f32_16x16x32_bf16 v[108:111], v[128:131], v[168:171], v[108:111]
	v_mfma_f32_16x16x32_bf16 v[92:95], v[128:131], v[192:195], v[92:95]
	v_mfma_f32_16x16x32_bf16 v[88:91], v[136:139], v[192:195], v[88:91]
	v_mfma_f32_16x16x32_bf16 v[72:75], v[136:139], v[200:203], v[72:75]
	v_mfma_f32_16x16x32_bf16 v[76:79], v[128:131], v[200:203], v[76:79]
	v_mfma_f32_16x16x32_bf16 v[124:127], v[132:135], v[164:167], v[124:127]
	v_mfma_f32_16x16x32_bf16 v[120:123], v[140:143], v[164:167], v[120:123]
	v_mfma_f32_16x16x32_bf16 v[104:107], v[140:143], v[172:175], v[104:107]
	v_mfma_f32_16x16x32_bf16 v[108:111], v[132:135], v[172:175], v[108:111]
	v_mfma_f32_16x16x32_bf16 v[92:95], v[132:135], v[196:199], v[92:95]
	v_mfma_f32_16x16x32_bf16 v[88:91], v[140:143], v[196:199], v[88:91]
	v_mfma_f32_16x16x32_bf16 v[72:75], v[140:143], v[212:215], v[72:75]
	v_mfma_f32_16x16x32_bf16 v[76:79], v[132:135], v[212:215], v[76:79]
	s_setprio 0
	s_setprio 1
	v_mfma_f32_16x16x32_bf16 v[116:119], v[144:147], v[160:163], v[116:119]
	v_mfma_f32_16x16x32_bf16 v[112:115], v[152:155], v[160:163], v[112:115]
	v_mfma_f32_16x16x32_bf16 v[96:99], v[152:155], v[168:171], v[96:99]
	v_mfma_f32_16x16x32_bf16 v[100:103], v[144:147], v[168:171], v[100:103]
	v_mfma_f32_16x16x32_bf16 v[84:87], v[144:147], v[192:195], v[84:87]
	v_mfma_f32_16x16x32_bf16 v[80:83], v[152:155], v[192:195], v[80:83]
	v_mfma_f32_16x16x32_bf16 v[64:67], v[152:155], v[200:203], v[64:67]
	v_mfma_f32_16x16x32_bf16 v[68:71], v[144:147], v[200:203], v[68:71]
	v_mfma_f32_16x16x32_bf16 v[116:119], v[148:151], v[164:167], v[116:119]
	v_mfma_f32_16x16x32_bf16 v[112:115], v[156:159], v[164:167], v[112:115]
	v_mfma_f32_16x16x32_bf16 v[96:99], v[156:159], v[172:175], v[96:99]
	v_mfma_f32_16x16x32_bf16 v[100:103], v[148:151], v[172:175], v[100:103]
	v_mfma_f32_16x16x32_bf16 v[84:87], v[148:151], v[196:199], v[84:87]
	v_mfma_f32_16x16x32_bf16 v[80:83], v[156:159], v[196:199], v[80:83]
	v_mfma_f32_16x16x32_bf16 v[64:67], v[156:159], v[212:215], v[64:67]
	v_mfma_f32_16x16x32_bf16 v[68:71], v[148:151], v[212:215], v[68:71]
	s_setprio 0
	s_barrier
	s_add_i32 s50, s35, s17
	v_lshl_add_u64 v[204:205], s[0:1], 0, v[178:179]
	s_mov_b32 m0, s50
	ds_read_b128 v[160:163], v211 offset:16384
	ds_read_b128 v[164:167], v211 offset:17408
	ds_read_b128 v[168:171], v211 offset:18432
	ds_read_b128 v[172:175], v211 offset:19456
	ds_read_b128 v[192:195], v211 offset:20480
	ds_read_b128 v[196:199], v211 offset:21504
	ds_read_b128 v[200:203], v211 offset:22528
	ds_read_b128 v[212:215], v211 offset:23552
	global_load_lds_dwordx4 v[204:205], off
	s_add_i32 m0, s50, 0x2000
	s_add_u32 s50, s0, 0x40000
	v_lshl_add_u64 v[216:217], s[0:1], 0, v[182:183]
	s_addc_u32 s51, s1, 0
	s_add_i32 s59, s44, s17
	global_load_lds_dwordx4 v[216:217], off
	v_lshl_add_u64 v[218:219], s[50:51], 0, v[178:179]
	s_mov_b32 m0, s59
	v_lshl_add_u64 v[220:221], s[64:65], 0, v[180:181]
	global_load_lds_dwordx4 v[218:219], off
	v_lshl_add_u64 v[218:219], s[50:51], 0, v[182:183]
	s_add_i32 m0, s59, 0x2000
	s_nop 0
	global_load_lds_dwordx4 v[218:219], off
	v_lshl_add_u64 v[218:219], s[64:65], 0, v[176:177]
	s_mov_b32 m0, s18
	s_nop 0
	global_load_lds_dwordx4 v[218:219], off
	s_mov_b32 m0, s19
	s_nop 0
	global_load_lds_dwordx4 v[220:221], off
	s_waitcnt vmcnt(8)
	s_waitcnt lgkmcnt(0)
	s_barrier
	s_setprio 1
	s_waitcnt lgkmcnt(0)
	v_mfma_f32_16x16x32_bf16 v[60:63], v[128:131], v[160:163], v[60:63]
	v_mfma_f32_16x16x32_bf16 v[56:59], v[136:139], v[160:163], v[56:59]
	v_mfma_f32_16x16x32_bf16 v[40:43], v[136:139], v[168:171], v[40:43]
	v_mfma_f32_16x16x32_bf16 v[44:47], v[128:131], v[168:171], v[44:47]
	v_mfma_f32_16x16x32_bf16 v[28:31], v[128:131], v[192:195], v[28:31]
	v_mfma_f32_16x16x32_bf16 v[24:27], v[136:139], v[192:195], v[24:27]
	v_mfma_f32_16x16x32_bf16 v[8:11], v[136:139], v[200:203], v[8:11]
	v_mfma_f32_16x16x32_bf16 v[12:15], v[128:131], v[200:203], v[12:15]
	v_mfma_f32_16x16x32_bf16 v[60:63], v[132:135], v[164:167], v[60:63]
	v_mfma_f32_16x16x32_bf16 v[56:59], v[140:143], v[164:167], v[56:59]
	v_mfma_f32_16x16x32_bf16 v[40:43], v[140:143], v[172:175], v[40:43]
	v_mfma_f32_16x16x32_bf16 v[44:47], v[132:135], v[172:175], v[44:47]
	v_mfma_f32_16x16x32_bf16 v[28:31], v[132:135], v[196:199], v[28:31]
	v_mfma_f32_16x16x32_bf16 v[24:27], v[140:143], v[196:199], v[24:27]
	v_mfma_f32_16x16x32_bf16 v[8:11], v[140:143], v[212:215], v[8:11]
	v_mfma_f32_16x16x32_bf16 v[12:15], v[132:135], v[212:215], v[12:15]
	s_setprio 0
	s_setprio 1
	v_mfma_f32_16x16x32_bf16 v[52:55], v[144:147], v[160:163], v[52:55]
	v_mfma_f32_16x16x32_bf16 v[48:51], v[152:155], v[160:163], v[48:51]
	v_mfma_f32_16x16x32_bf16 v[32:35], v[152:155], v[168:171], v[32:35]
	v_mfma_f32_16x16x32_bf16 v[36:39], v[144:147], v[168:171], v[36:39]
	v_mfma_f32_16x16x32_bf16 v[20:23], v[144:147], v[192:195], v[20:23]
	v_mfma_f32_16x16x32_bf16 v[16:19], v[152:155], v[192:195], v[16:19]
	v_mfma_f32_16x16x32_bf16 v[0:3], v[152:155], v[200:203], v[0:3]
	v_mfma_f32_16x16x32_bf16 v[4:7], v[144:147], v[200:203], v[4:7]
	v_mfma_f32_16x16x32_bf16 v[52:55], v[148:151], v[164:167], v[52:55]
	v_mfma_f32_16x16x32_bf16 v[48:51], v[156:159], v[164:167], v[48:51]
	v_mfma_f32_16x16x32_bf16 v[32:35], v[156:159], v[172:175], v[32:35]
	v_mfma_f32_16x16x32_bf16 v[36:39], v[148:151], v[172:175], v[36:39]
	v_mfma_f32_16x16x32_bf16 v[20:23], v[148:151], v[196:199], v[20:23]
	v_mfma_f32_16x16x32_bf16 v[16:19], v[156:159], v[196:199], v[16:19]
	v_mfma_f32_16x16x32_bf16 v[0:3], v[156:159], v[212:215], v[0:3]
	v_mfma_f32_16x16x32_bf16 v[4:7], v[148:151], v[212:215], v[4:7]
	s_setprio 0
	s_barrier
	s_add_i32 s59, 0, 0x18000
	s_add_i32 s61, 0, 0x1c000
	v_add_u32_e32 v140, s59, v207
	v_add_u32_e32 v156, s61, v207
	ds_read_b128 v[128:131], v140
	ds_read_b128 v[132:135], v140 offset:1024
	ds_read_b128 v[136:139], v140 offset:2048
	ds_read_b128 v[140:143], v140 offset:3072
	ds_read_b128 v[144:147], v156
	ds_read_b128 v[148:151], v156 offset:1024
	ds_read_b128 v[152:155], v156 offset:2048
	ds_read_b128 v[156:159], v156 offset:3072
	s_add_u32 s50, s64, 0x40000
	s_addc_u32 s51, s65, 0
	s_mov_b32 m0, s24
	v_lshl_add_u64 v[222:223], s[50:51], 0, v[176:177]
	ds_read_b128 v[160:163], v211 offset:32768
	ds_read_b128 v[164:167], v211 offset:33792
	ds_read_b128 v[168:171], v211 offset:34816
	ds_read_b128 v[172:175], v211 offset:35840
	ds_read_b128 v[192:195], v211 offset:36864
	ds_read_b128 v[196:199], v211 offset:37888
	ds_read_b128 v[200:203], v211 offset:38912
	ds_read_b128 v[212:215], v211 offset:39936
	global_load_lds_dwordx4 v[222:223], off
	v_lshl_add_u64 v[222:223], s[50:51], 0, v[180:181]
	s_mov_b32 m0, s25
	s_nop 0
	global_load_lds_dwordx4 v[222:223], off
	s_waitcnt vmcnt(8)
	s_waitcnt lgkmcnt(0)
	s_barrier
	s_setprio 1
	s_waitcnt lgkmcnt(0)
	v_mfma_f32_16x16x32_bf16 v[124:127], v[128:131], v[160:163], v[124:127]
	v_mfma_f32_16x16x32_bf16 v[120:123], v[136:139], v[160:163], v[120:123]
	v_mfma_f32_16x16x32_bf16 v[104:107], v[136:139], v[168:171], v[104:107]
	v_mfma_f32_16x16x32_bf16 v[108:111], v[128:131], v[168:171], v[108:111]
	v_mfma_f32_16x16x32_bf16 v[92:95], v[128:131], v[192:195], v[92:95]
	v_mfma_f32_16x16x32_bf16 v[88:91], v[136:139], v[192:195], v[88:91]
	v_mfma_f32_16x16x32_bf16 v[72:75], v[136:139], v[200:203], v[72:75]
	v_mfma_f32_16x16x32_bf16 v[76:79], v[128:131], v[200:203], v[76:79]
	v_mfma_f32_16x16x32_bf16 v[124:127], v[132:135], v[164:167], v[124:127]
	v_mfma_f32_16x16x32_bf16 v[120:123], v[140:143], v[164:167], v[120:123]
	v_mfma_f32_16x16x32_bf16 v[104:107], v[140:143], v[172:175], v[104:107]
	v_mfma_f32_16x16x32_bf16 v[108:111], v[132:135], v[172:175], v[108:111]
	v_mfma_f32_16x16x32_bf16 v[92:95], v[132:135], v[196:199], v[92:95]
	v_mfma_f32_16x16x32_bf16 v[88:91], v[140:143], v[196:199], v[88:91]
	v_mfma_f32_16x16x32_bf16 v[72:75], v[140:143], v[212:215], v[72:75]
	v_mfma_f32_16x16x32_bf16 v[76:79], v[132:135], v[212:215], v[76:79]
	s_setprio 0
	s_setprio 1
	v_mfma_f32_16x16x32_bf16 v[116:119], v[144:147], v[160:163], v[116:119]
	v_mfma_f32_16x16x32_bf16 v[112:115], v[152:155], v[160:163], v[112:115]
	v_mfma_f32_16x16x32_bf16 v[96:99], v[152:155], v[168:171], v[96:99]
	v_mfma_f32_16x16x32_bf16 v[100:103], v[144:147], v[168:171], v[100:103]
	v_mfma_f32_16x16x32_bf16 v[84:87], v[144:147], v[192:195], v[84:87]
	v_mfma_f32_16x16x32_bf16 v[80:83], v[152:155], v[192:195], v[80:83]
	v_mfma_f32_16x16x32_bf16 v[64:67], v[152:155], v[200:203], v[64:67]
	v_mfma_f32_16x16x32_bf16 v[68:71], v[144:147], v[200:203], v[68:71]
	v_mfma_f32_16x16x32_bf16 v[116:119], v[148:151], v[164:167], v[116:119]
	v_mfma_f32_16x16x32_bf16 v[112:115], v[156:159], v[164:167], v[112:115]
	v_mfma_f32_16x16x32_bf16 v[96:99], v[156:159], v[172:175], v[96:99]
	v_mfma_f32_16x16x32_bf16 v[100:103], v[148:151], v[172:175], v[100:103]
	v_mfma_f32_16x16x32_bf16 v[84:87], v[148:151], v[196:199], v[84:87]
	v_mfma_f32_16x16x32_bf16 v[80:83], v[156:159], v[196:199], v[80:83]
	v_mfma_f32_16x16x32_bf16 v[64:67], v[156:159], v[212:215], v[64:67]
	v_mfma_f32_16x16x32_bf16 v[68:71], v[148:151], v[212:215], v[68:71]
	s_setprio 0
	s_barrier
	s_add_i32 s50, s59, s17
	v_lshl_add_u64 v[204:205], v[204:205], 0, s[14:15]
	s_mov_b32 m0, s50
	ds_read_b128 v[160:163], v211 offset:49152
	ds_read_b128 v[164:167], v211 offset:50176
	ds_read_b128 v[168:171], v211 offset:51200
	ds_read_b128 v[172:175], v211 offset:52224
	ds_read_b128 v[192:195], v211 offset:53248
	ds_read_b128 v[196:199], v211 offset:54272
	ds_read_b128 v[200:203], v211 offset:55296
	ds_read_b128 v[212:215], v211 offset:56320
	global_load_lds_dwordx4 v[204:205], off
	s_add_i32 m0, s50, 0x2000
	s_add_u32 s0, s0, 0x40080
	v_lshl_add_u64 v[204:205], v[216:217], 0, s[14:15]
	s_addc_u32 s1, s1, 0
	s_add_i32 s50, s61, s17
	global_load_lds_dwordx4 v[204:205], off
	v_lshl_add_u64 v[204:205], s[0:1], 0, v[178:179]
	s_mov_b32 m0, s50
	s_nop 0
	global_load_lds_dwordx4 v[204:205], off
	v_lshl_add_u64 v[204:205], s[0:1], 0, v[182:183]
	s_add_i32 m0, s50, 0x2000
	s_nop 0
	global_load_lds_dwordx4 v[204:205], off
	v_lshl_add_u64 v[204:205], v[218:219], 0, s[14:15]
	s_mov_b32 m0, s27
	s_nop 0
	global_load_lds_dwordx4 v[204:205], off
	v_lshl_add_u64 v[204:205], v[220:221], 0, s[14:15]
	s_mov_b32 m0, s30
	s_nop 0
	global_load_lds_dwordx4 v[204:205], off
	s_waitcnt vmcnt(8)
	s_waitcnt lgkmcnt(0)
	s_barrier
	s_setprio 1
	s_waitcnt lgkmcnt(0)
	v_mfma_f32_16x16x32_bf16 v[60:63], v[128:131], v[160:163], v[60:63]
	v_mfma_f32_16x16x32_bf16 v[56:59], v[136:139], v[160:163], v[56:59]
	v_mfma_f32_16x16x32_bf16 v[40:43], v[136:139], v[168:171], v[40:43]
	v_mfma_f32_16x16x32_bf16 v[44:47], v[128:131], v[168:171], v[44:47]
	v_mfma_f32_16x16x32_bf16 v[28:31], v[128:131], v[192:195], v[28:31]
	v_mfma_f32_16x16x32_bf16 v[24:27], v[136:139], v[192:195], v[24:27]
	v_mfma_f32_16x16x32_bf16 v[8:11], v[136:139], v[200:203], v[8:11]
	v_mfma_f32_16x16x32_bf16 v[12:15], v[128:131], v[200:203], v[12:15]
	v_mfma_f32_16x16x32_bf16 v[60:63], v[132:135], v[164:167], v[60:63]
	v_mfma_f32_16x16x32_bf16 v[56:59], v[140:143], v[164:167], v[56:59]
	v_mfma_f32_16x16x32_bf16 v[40:43], v[140:143], v[172:175], v[40:43]
	v_mfma_f32_16x16x32_bf16 v[44:47], v[132:135], v[172:175], v[44:47]
	v_mfma_f32_16x16x32_bf16 v[28:31], v[132:135], v[196:199], v[28:31]
	v_mfma_f32_16x16x32_bf16 v[24:27], v[140:143], v[196:199], v[24:27]
	v_mfma_f32_16x16x32_bf16 v[8:11], v[140:143], v[212:215], v[8:11]
	v_mfma_f32_16x16x32_bf16 v[12:15], v[132:135], v[212:215], v[12:15]
	s_setprio 0
	s_setprio 1
	v_mfma_f32_16x16x32_bf16 v[52:55], v[144:147], v[160:163], v[52:55]
	v_mfma_f32_16x16x32_bf16 v[48:51], v[152:155], v[160:163], v[48:51]
	v_mfma_f32_16x16x32_bf16 v[32:35], v[152:155], v[168:171], v[32:35]
	v_mfma_f32_16x16x32_bf16 v[36:39], v[144:147], v[168:171], v[36:39]
	v_mfma_f32_16x16x32_bf16 v[20:23], v[144:147], v[192:195], v[20:23]
	v_mfma_f32_16x16x32_bf16 v[16:19], v[152:155], v[192:195], v[16:19]
	v_mfma_f32_16x16x32_bf16 v[0:3], v[152:155], v[200:203], v[0:3]
	v_mfma_f32_16x16x32_bf16 v[4:7], v[144:147], v[200:203], v[4:7]
	v_mfma_f32_16x16x32_bf16 v[52:55], v[148:151], v[164:167], v[52:55]
	v_mfma_f32_16x16x32_bf16 v[48:51], v[156:159], v[164:167], v[48:51]
	v_mfma_f32_16x16x32_bf16 v[32:35], v[156:159], v[172:175], v[32:35]
	v_mfma_f32_16x16x32_bf16 v[36:39], v[148:151], v[172:175], v[36:39]
	v_mfma_f32_16x16x32_bf16 v[20:23], v[148:151], v[196:199], v[20:23]
	v_mfma_f32_16x16x32_bf16 v[16:19], v[156:159], v[196:199], v[16:19]
	v_mfma_f32_16x16x32_bf16 v[0:3], v[156:159], v[212:215], v[0:3]
	v_mfma_f32_16x16x32_bf16 v[4:7], v[148:151], v[212:215], v[4:7]
	s_setprio 0
	s_barrier
	s_add_i32 s49, s49, 2
	s_add_u32 s62, s62, 0x100
	s_addc_u32 s63, s63, 0
	s_add_u32 s46, s46, 0x100
	s_addc_u32 s47, s47, 0
	s_cmp_gt_u32 s49, 13
	s_cbranch_scc0 .LBB0_617
	s_and_b64 vcc, exec, s[40:41]
	s_cbranch_vccz .LBB0_620
	s_barrier

.LBB0_701:
	ds_read_b128 v[60:63], v190
	ds_read_b128 v[68:71], v190 offset:1024
	ds_read_b128 v[72:75], v190 offset:2048
	ds_read_b128 v[76:79], v190 offset:3072
	ds_read_b128 v[80:83], v191
	ds_read_b128 v[84:87], v191 offset:1024
	ds_read_b128 v[88:91], v191 offset:2048
	ds_read_b128 v[92:95], v191 offset:3072
	s_add_u32 s0, s68, 0xfffc0080
	s_addc_u32 s1, s69, -1
	s_cmp_eq_u32 s61, 12
	s_cselect_b32 s71, s19, s1
	s_cselect_b32 s70, s24, s0
	s_cselect_b32 s1, s25, s59
	s_cselect_b32 s0, s38, s39
	v_lshl_add_u64 v[220:221], s[68:69], 0, v[172:173]
	s_add_i32 m0, s31, 0xc000
	ds_read_b128 v[180:183], v192
	ds_read_b128 v[184:187], v192 offset:1024
	ds_read_b128 v[196:199], v192 offset:2048
	ds_read_b128 v[200:203], v192 offset:3072
	ds_read_b128 v[204:207], v192 offset:4096
	ds_read_b128 v[208:211], v192 offset:5120
	ds_read_b128 v[212:215], v192 offset:6144
	ds_read_b128 v[216:219], v192 offset:7168
	global_load_lds_dwordx4 v[220:221], off
	v_lshl_add_u64 v[220:221], s[68:69], 0, v[174:175]
	s_add_i32 m0, s31, 0xe000
	s_nop 0
	global_load_lds_dwordx4 v[220:221], off
	s_waitcnt vmcnt(8)
	s_waitcnt lgkmcnt(0)
	s_barrier
	s_setprio 1
	s_waitcnt lgkmcnt(0)
	v_mfma_f32_16x16x32_bf16 v[156:159], v[60:63], v[180:183], v[156:159]
	v_mfma_f32_16x16x32_bf16 v[152:155], v[72:75], v[180:183], v[152:155]
	v_mfma_f32_16x16x32_bf16 v[136:139], v[72:75], v[196:199], v[136:139]
	v_mfma_f32_16x16x32_bf16 v[140:143], v[60:63], v[196:199], v[140:143]
	v_mfma_f32_16x16x32_bf16 v[124:127], v[60:63], v[204:207], v[124:127]
	v_mfma_f32_16x16x32_bf16 v[120:123], v[72:75], v[204:207], v[120:123]
	v_mfma_f32_16x16x32_bf16 v[104:107], v[72:75], v[212:215], v[104:107]
	v_mfma_f32_16x16x32_bf16 v[108:111], v[60:63], v[212:215], v[108:111]
	v_mfma_f32_16x16x32_bf16 v[156:159], v[68:71], v[184:187], v[156:159]
	v_mfma_f32_16x16x32_bf16 v[152:155], v[76:79], v[184:187], v[152:155]
	v_mfma_f32_16x16x32_bf16 v[136:139], v[76:79], v[200:203], v[136:139]
	v_mfma_f32_16x16x32_bf16 v[140:143], v[68:71], v[200:203], v[140:143]
	v_mfma_f32_16x16x32_bf16 v[124:127], v[68:71], v[208:211], v[124:127]
	v_mfma_f32_16x16x32_bf16 v[120:123], v[76:79], v[208:211], v[120:123]
	v_mfma_f32_16x16x32_bf16 v[104:107], v[76:79], v[216:219], v[104:107]
	v_mfma_f32_16x16x32_bf16 v[108:111], v[68:71], v[216:219], v[108:111]
	s_setprio 0
	s_setprio 1
	v_mfma_f32_16x16x32_bf16 v[148:151], v[80:83], v[180:183], v[148:151]
	v_mfma_f32_16x16x32_bf16 v[144:147], v[88:91], v[180:183], v[144:147]
	v_mfma_f32_16x16x32_bf16 v[128:131], v[88:91], v[196:199], v[128:131]
	v_mfma_f32_16x16x32_bf16 v[132:135], v[80:83], v[196:199], v[132:135]
	v_mfma_f32_16x16x32_bf16 v[116:119], v[80:83], v[204:207], v[116:119]
	v_mfma_f32_16x16x32_bf16 v[112:115], v[88:91], v[204:207], v[112:115]
	v_mfma_f32_16x16x32_bf16 v[96:99], v[88:91], v[212:215], v[96:99]
	v_mfma_f32_16x16x32_bf16 v[100:103], v[80:83], v[212:215], v[100:103]
	v_mfma_f32_16x16x32_bf16 v[148:151], v[84:87], v[184:187], v[148:151]
	v_mfma_f32_16x16x32_bf16 v[144:147], v[92:95], v[184:187], v[144:147]
	v_mfma_f32_16x16x32_bf16 v[128:131], v[92:95], v[200:203], v[128:131]
	v_mfma_f32_16x16x32_bf16 v[132:135], v[84:87], v[200:203], v[132:135]
	v_mfma_f32_16x16x32_bf16 v[116:119], v[84:87], v[208:211], v[116:119]
	v_mfma_f32_16x16x32_bf16 v[112:115], v[92:95], v[208:211], v[112:115]
	v_mfma_f32_16x16x32_bf16 v[96:99], v[92:95], v[216:219], v[96:99]
	v_mfma_f32_16x16x32_bf16 v[100:103], v[84:87], v[216:219], v[100:103]
	s_setprio 0
	s_barrier
	s_add_i32 s67, s55, s26
	v_lshl_add_u64 v[220:221], s[0:1], 0, v[164:165]
	s_mov_b32 m0, s67
	ds_read_b128 v[180:183], v192 offset:16384
	ds_read_b128 v[184:187], v192 offset:17408
	ds_read_b128 v[196:199], v192 offset:18432
	ds_read_b128 v[200:203], v192 offset:19456
	ds_read_b128 v[204:207], v192 offset:20480
	ds_read_b128 v[208:211], v192 offset:21504
	ds_read_b128 v[212:215], v192 offset:22528
	ds_read_b128 v[216:219], v192 offset:23552
	global_load_lds_dwordx4 v[220:221], off
	s_add_i32 m0, s67, 0x2000
	s_add_u32 s74, s0, 0x40000
	v_lshl_add_u64 v[222:223], s[0:1], 0, v[160:161]
	s_addc_u32 s75, s1, 0
	s_add_i32 s67, s57, s26
	global_load_lds_dwordx4 v[222:223], off
	v_lshl_add_u64 v[224:225], s[74:75], 0, v[164:165]
	s_mov_b32 m0, s67
	v_lshl_add_u64 v[226:227], s[70:71], 0, v[162:163]
	global_load_lds_dwordx4 v[224:225], off
	v_lshl_add_u64 v[224:225], s[74:75], 0, v[160:161]
	s_add_i32 m0, s67, 0x2000
	s_nop 0
	global_load_lds_dwordx4 v[224:225], off
	v_lshl_add_u64 v[224:225], s[70:71], 0, v[166:167]
	s_mov_b32 m0, s31
	s_nop 0
	global_load_lds_dwordx4 v[224:225], off
	s_mov_b32 m0, s33
	s_nop 0
	global_load_lds_dwordx4 v[226:227], off
	s_waitcnt vmcnt(8)
	s_waitcnt lgkmcnt(0)
	s_barrier
	s_setprio 1
	s_waitcnt lgkmcnt(0)
	v_mfma_f32_16x16x32_bf16 v[64:67], v[60:63], v[180:183], v[64:67]
	v_mfma_f32_16x16x32_bf16 v[56:59], v[72:75], v[180:183], v[56:59]
	v_mfma_f32_16x16x32_bf16 v[40:43], v[72:75], v[196:199], v[40:43]
	v_mfma_f32_16x16x32_bf16 v[44:47], v[60:63], v[196:199], v[44:47]
	v_mfma_f32_16x16x32_bf16 v[28:31], v[60:63], v[204:207], v[28:31]
	v_mfma_f32_16x16x32_bf16 v[24:27], v[72:75], v[204:207], v[24:27]
	v_mfma_f32_16x16x32_bf16 v[8:11], v[72:75], v[212:215], v[8:11]
	v_mfma_f32_16x16x32_bf16 v[12:15], v[60:63], v[212:215], v[12:15]
	v_mfma_f32_16x16x32_bf16 v[64:67], v[68:71], v[184:187], v[64:67]
	v_mfma_f32_16x16x32_bf16 v[56:59], v[76:79], v[184:187], v[56:59]
	v_mfma_f32_16x16x32_bf16 v[40:43], v[76:79], v[200:203], v[40:43]
	v_mfma_f32_16x16x32_bf16 v[44:47], v[68:71], v[200:203], v[44:47]
	v_mfma_f32_16x16x32_bf16 v[28:31], v[68:71], v[208:211], v[28:31]
	v_mfma_f32_16x16x32_bf16 v[24:27], v[76:79], v[208:211], v[24:27]
	v_mfma_f32_16x16x32_bf16 v[8:11], v[76:79], v[216:219], v[8:11]
	v_mfma_f32_16x16x32_bf16 v[12:15], v[68:71], v[216:219], v[12:15]
	s_setprio 0
	s_setprio 1
	v_mfma_f32_16x16x32_bf16 v[52:55], v[80:83], v[180:183], v[52:55]
	v_mfma_f32_16x16x32_bf16 v[48:51], v[88:91], v[180:183], v[48:51]
	v_mfma_f32_16x16x32_bf16 v[32:35], v[88:91], v[196:199], v[32:35]
	v_mfma_f32_16x16x32_bf16 v[36:39], v[80:83], v[196:199], v[36:39]
	v_mfma_f32_16x16x32_bf16 v[20:23], v[80:83], v[204:207], v[20:23]
	v_mfma_f32_16x16x32_bf16 v[16:19], v[88:91], v[204:207], v[16:19]
	v_mfma_f32_16x16x32_bf16 v[0:3], v[88:91], v[212:215], v[0:3]
	v_mfma_f32_16x16x32_bf16 v[4:7], v[80:83], v[212:215], v[4:7]
	v_mfma_f32_16x16x32_bf16 v[52:55], v[84:87], v[184:187], v[52:55]
	v_mfma_f32_16x16x32_bf16 v[48:51], v[92:95], v[184:187], v[48:51]
	v_mfma_f32_16x16x32_bf16 v[32:35], v[92:95], v[200:203], v[32:35]
	v_mfma_f32_16x16x32_bf16 v[36:39], v[84:87], v[200:203], v[36:39]
	v_mfma_f32_16x16x32_bf16 v[20:23], v[84:87], v[208:211], v[20:23]
	v_mfma_f32_16x16x32_bf16 v[16:19], v[92:95], v[208:211], v[16:19]
	v_mfma_f32_16x16x32_bf16 v[0:3], v[92:95], v[216:219], v[0:3]
	v_mfma_f32_16x16x32_bf16 v[4:7], v[84:87], v[216:219], v[4:7]
	s_setprio 0
	s_barrier
	s_add_i32 s67, 0, 0x18000
	s_add_i32 s73, 0, 0x1c000
	v_add_u32_e32 v76, s67, v169
	v_add_u32_e32 v92, s73, v169
	ds_read_b128 v[60:63], v76
	ds_read_b128 v[68:71], v76 offset:1024
	ds_read_b128 v[72:75], v76 offset:2048
	ds_read_b128 v[76:79], v76 offset:3072
	ds_read_b128 v[80:83], v92
	ds_read_b128 v[84:87], v92 offset:1024
	ds_read_b128 v[88:91], v92 offset:2048
	ds_read_b128 v[92:95], v92 offset:3072
	s_add_u32 s70, s70, 0x40000
	s_addc_u32 s71, s71, 0
	s_mov_b32 m0, s34
	v_lshl_add_u64 v[228:229], s[70:71], 0, v[166:167]
	ds_read_b128 v[180:183], v192 offset:32768
	ds_read_b128 v[184:187], v192 offset:33792
	ds_read_b128 v[196:199], v192 offset:34816
	ds_read_b128 v[200:203], v192 offset:35840
	ds_read_b128 v[204:207], v192 offset:36864
	ds_read_b128 v[208:211], v192 offset:37888
	ds_read_b128 v[212:215], v192 offset:38912
	ds_read_b128 v[216:219], v192 offset:39936
	global_load_lds_dwordx4 v[228:229], off
	v_lshl_add_u64 v[228:229], s[70:71], 0, v[162:163]
	s_mov_b32 m0, s35
	s_nop 0
	global_load_lds_dwordx4 v[228:229], off
	s_waitcnt vmcnt(8)
	s_waitcnt lgkmcnt(0)
	s_barrier
	s_setprio 1
	s_waitcnt lgkmcnt(0)
	v_mfma_f32_16x16x32_bf16 v[156:159], v[60:63], v[180:183], v[156:159]
	v_mfma_f32_16x16x32_bf16 v[152:155], v[72:75], v[180:183], v[152:155]
	v_mfma_f32_16x16x32_bf16 v[136:139], v[72:75], v[196:199], v[136:139]
	v_mfma_f32_16x16x32_bf16 v[140:143], v[60:63], v[196:199], v[140:143]
	v_mfma_f32_16x16x32_bf16 v[124:127], v[60:63], v[204:207], v[124:127]
	v_mfma_f32_16x16x32_bf16 v[120:123], v[72:75], v[204:207], v[120:123]
	v_mfma_f32_16x16x32_bf16 v[104:107], v[72:75], v[212:215], v[104:107]
	v_mfma_f32_16x16x32_bf16 v[108:111], v[60:63], v[212:215], v[108:111]
	v_mfma_f32_16x16x32_bf16 v[156:159], v[68:71], v[184:187], v[156:159]
	v_mfma_f32_16x16x32_bf16 v[152:155], v[76:79], v[184:187], v[152:155]
	v_mfma_f32_16x16x32_bf16 v[136:139], v[76:79], v[200:203], v[136:139]
	v_mfma_f32_16x16x32_bf16 v[140:143], v[68:71], v[200:203], v[140:143]
	v_mfma_f32_16x16x32_bf16 v[124:127], v[68:71], v[208:211], v[124:127]
	v_mfma_f32_16x16x32_bf16 v[120:123], v[76:79], v[208:211], v[120:123]
	v_mfma_f32_16x16x32_bf16 v[104:107], v[76:79], v[216:219], v[104:107]
	v_mfma_f32_16x16x32_bf16 v[108:111], v[68:71], v[216:219], v[108:111]
	s_setprio 0
	s_setprio 1
	v_mfma_f32_16x16x32_bf16 v[148:151], v[80:83], v[180:183], v[148:151]
	v_mfma_f32_16x16x32_bf16 v[144:147], v[88:91], v[180:183], v[144:147]
	v_mfma_f32_16x16x32_bf16 v[128:131], v[88:91], v[196:199], v[128:131]
	v_mfma_f32_16x16x32_bf16 v[132:135], v[80:83], v[196:199], v[132:135]
	v_mfma_f32_16x16x32_bf16 v[116:119], v[80:83], v[204:207], v[116:119]
	v_mfma_f32_16x16x32_bf16 v[112:115], v[88:91], v[204:207], v[112:115]
	v_mfma_f32_16x16x32_bf16 v[96:99], v[88:91], v[212:215], v[96:99]
	v_mfma_f32_16x16x32_bf16 v[100:103], v[80:83], v[212:215], v[100:103]
	v_mfma_f32_16x16x32_bf16 v[148:151], v[84:87], v[184:187], v[148:151]
	v_mfma_f32_16x16x32_bf16 v[144:147], v[92:95], v[184:187], v[144:147]
	v_mfma_f32_16x16x32_bf16 v[128:131], v[92:95], v[200:203], v[128:131]
	v_mfma_f32_16x16x32_bf16 v[132:135], v[84:87], v[200:203], v[132:135]
	v_mfma_f32_16x16x32_bf16 v[116:119], v[84:87], v[208:211], v[116:119]
	v_mfma_f32_16x16x32_bf16 v[112:115], v[92:95], v[208:211], v[112:115]
	v_mfma_f32_16x16x32_bf16 v[96:99], v[92:95], v[216:219], v[96:99]
	v_mfma_f32_16x16x32_bf16 v[100:103], v[84:87], v[216:219], v[100:103]
	s_setprio 0
	s_barrier
	s_add_i32 s67, s67, s26
	v_lshl_add_u64 v[220:221], v[220:221], 0, s[80:81]
	s_mov_b32 m0, s67
	ds_read_b128 v[180:183], v192 offset:49152
	ds_read_b128 v[184:187], v192 offset:50176
	ds_read_b128 v[196:199], v192 offset:51200
	ds_read_b128 v[200:203], v192 offset:52224
	ds_read_b128 v[204:207], v192 offset:53248
	ds_read_b128 v[208:211], v192 offset:54272
	ds_read_b128 v[212:215], v192 offset:55296
	ds_read_b128 v[216:219], v192 offset:56320
	global_load_lds_dwordx4 v[220:221], off
	s_add_i32 m0, s67, 0x2000
	s_add_u32 s0, s0, 0x40080
	v_lshl_add_u64 v[220:221], v[222:223], 0, s[80:81]
	s_addc_u32 s1, s1, 0
	s_add_i32 s67, s73, s26
	global_load_lds_dwordx4 v[220:221], off
	v_lshl_add_u64 v[220:221], s[0:1], 0, v[164:165]
	s_mov_b32 m0, s67
	s_nop 0
	global_load_lds_dwordx4 v[220:221], off
	v_lshl_add_u64 v[220:221], s[0:1], 0, v[160:161]
	s_add_i32 m0, s67, 0x2000
	s_nop 0
	global_load_lds_dwordx4 v[220:221], off
	v_lshl_add_u64 v[220:221], v[224:225], 0, s[80:81]
	s_mov_b32 m0, s76
	s_nop 0
	global_load_lds_dwordx4 v[220:221], off
	v_lshl_add_u64 v[220:221], v[226:227], 0, s[80:81]
	s_mov_b32 m0, s77
	s_nop 0
	global_load_lds_dwordx4 v[220:221], off
	s_waitcnt vmcnt(8)
	s_waitcnt lgkmcnt(0)
	s_barrier
	s_setprio 1
	s_waitcnt lgkmcnt(0)
	v_mfma_f32_16x16x32_bf16 v[64:67], v[60:63], v[180:183], v[64:67]
	v_mfma_f32_16x16x32_bf16 v[56:59], v[72:75], v[180:183], v[56:59]
	v_mfma_f32_16x16x32_bf16 v[40:43], v[72:75], v[196:199], v[40:43]
	v_mfma_f32_16x16x32_bf16 v[44:47], v[60:63], v[196:199], v[44:47]
	v_mfma_f32_16x16x32_bf16 v[28:31], v[60:63], v[204:207], v[28:31]
	v_mfma_f32_16x16x32_bf16 v[24:27], v[72:75], v[204:207], v[24:27]
	v_mfma_f32_16x16x32_bf16 v[8:11], v[72:75], v[212:215], v[8:11]
	v_mfma_f32_16x16x32_bf16 v[12:15], v[60:63], v[212:215], v[12:15]
	v_mfma_f32_16x16x32_bf16 v[64:67], v[68:71], v[184:187], v[64:67]
	v_mfma_f32_16x16x32_bf16 v[56:59], v[76:79], v[184:187], v[56:59]
	v_mfma_f32_16x16x32_bf16 v[40:43], v[76:79], v[200:203], v[40:43]
	v_mfma_f32_16x16x32_bf16 v[44:47], v[68:71], v[200:203], v[44:47]
	v_mfma_f32_16x16x32_bf16 v[28:31], v[68:71], v[208:211], v[28:31]
	v_mfma_f32_16x16x32_bf16 v[24:27], v[76:79], v[208:211], v[24:27]
	v_mfma_f32_16x16x32_bf16 v[8:11], v[76:79], v[216:219], v[8:11]
	v_mfma_f32_16x16x32_bf16 v[12:15], v[68:71], v[216:219], v[12:15]
	s_setprio 0
	s_setprio 1
	v_mfma_f32_16x16x32_bf16 v[52:55], v[80:83], v[180:183], v[52:55]
	v_mfma_f32_16x16x32_bf16 v[48:51], v[88:91], v[180:183], v[48:51]
	v_mfma_f32_16x16x32_bf16 v[32:35], v[88:91], v[196:199], v[32:35]
	v_mfma_f32_16x16x32_bf16 v[36:39], v[80:83], v[196:199], v[36:39]
	v_mfma_f32_16x16x32_bf16 v[20:23], v[80:83], v[204:207], v[20:23]
	v_mfma_f32_16x16x32_bf16 v[16:19], v[88:91], v[204:207], v[16:19]
	v_mfma_f32_16x16x32_bf16 v[0:3], v[88:91], v[212:215], v[0:3]
	v_mfma_f32_16x16x32_bf16 v[4:7], v[80:83], v[212:215], v[4:7]
	v_mfma_f32_16x16x32_bf16 v[52:55], v[84:87], v[184:187], v[52:55]
	v_mfma_f32_16x16x32_bf16 v[48:51], v[92:95], v[184:187], v[48:51]
	v_mfma_f32_16x16x32_bf16 v[32:35], v[92:95], v[200:203], v[32:35]
	v_mfma_f32_16x16x32_bf16 v[36:39], v[84:87], v[200:203], v[36:39]
	v_mfma_f32_16x16x32_bf16 v[20:23], v[84:87], v[208:211], v[20:23]
	v_mfma_f32_16x16x32_bf16 v[16:19], v[92:95], v[208:211], v[16:19]
	v_mfma_f32_16x16x32_bf16 v[0:3], v[92:95], v[216:219], v[0:3]
	v_mfma_f32_16x16x32_bf16 v[4:7], v[84:87], v[216:219], v[4:7]
	s_setprio 0
	s_barrier
	s_add_i32 s61, s61, 2
	s_add_u32 s68, s68, 0x100
	s_addc_u32 s69, s69, 0
	s_add_u32 s39, s39, 0x100
	s_addc_u32 s59, s59, 0
	s_cmp_gt_u32 s61, 13
	s_cbranch_scc0 .LBB0_701
	s_and_b64 vcc, exec, s[82:83]
	s_cbranch_vccz .LBB0_704
	s_barrier

.LBB0_851:
	ds_read_b128 v[120:123], v250
	ds_read_b128 v[124:127], v250 offset:1024
	ds_read_b128 v[136:139], v250 offset:2048
	ds_read_b128 v[140:143], v250 offset:3072
	ds_read_b128 v[144:147], v251
	ds_read_b128 v[148:151], v251 offset:1024
	ds_read_b128 v[152:155], v251 offset:2048
	ds_read_b128 v[156:159], v251 offset:3072
	s_add_u32 s44, s42, 0x100
	s_addc_u32 s45, s43, 0
	s_cmp_eq_u32 s57, 44
	s_cselect_b32 s47, s9, s45
	s_cselect_b32 s46, s8, s44
	s_cselect_b32 s1, s41, s56
	s_cselect_b32 s0, s40, s55
	v_lshl_add_u64 v[208:209], s[42:43], 0, v[200:201]
	s_add_i32 m0, s24, 0xc000
	ds_read_b128 v[160:163], v252
	ds_read_b128 v[164:167], v252 offset:1024
	ds_read_b128 v[168:171], v252 offset:2048
	ds_read_b128 v[172:175], v252 offset:3072
	ds_read_b128 v[176:179], v252 offset:4096
	ds_read_b128 v[180:183], v252 offset:5120
	ds_read_b128 v[184:187], v252 offset:6144
	ds_read_b128 v[188:191], v252 offset:7168
	global_load_lds_dwordx4 v[208:209], off
	v_lshl_add_u64 v[208:209], s[42:43], 0, v[202:203]
	s_add_i32 m0, s24, 0xe000
	s_nop 0
	global_load_lds_dwordx4 v[208:209], off
	s_waitcnt vmcnt(8)
	s_waitcnt lgkmcnt(0)
	s_barrier
	s_setprio 1
	s_waitcnt lgkmcnt(0)
	v_mfma_f32_16x16x32_bf16 v[132:135], v[120:123], v[160:163], v[132:135]
	v_mfma_f32_16x16x32_bf16 v[128:131], v[136:139], v[160:163], v[128:131]
	v_mfma_f32_16x16x32_bf16 v[104:107], v[136:139], v[168:171], v[104:107]
	v_mfma_f32_16x16x32_bf16 v[108:111], v[120:123], v[168:171], v[108:111]
	v_mfma_f32_16x16x32_bf16 v[92:95], v[120:123], v[176:179], v[92:95]
	v_mfma_f32_16x16x32_bf16 v[88:91], v[136:139], v[176:179], v[88:91]
	v_mfma_f32_16x16x32_bf16 v[72:75], v[136:139], v[184:187], v[72:75]
	v_mfma_f32_16x16x32_bf16 v[76:79], v[120:123], v[184:187], v[76:79]
	v_mfma_f32_16x16x32_bf16 v[132:135], v[124:127], v[164:167], v[132:135]
	v_mfma_f32_16x16x32_bf16 v[128:131], v[140:143], v[164:167], v[128:131]
	v_mfma_f32_16x16x32_bf16 v[104:107], v[140:143], v[172:175], v[104:107]
	v_mfma_f32_16x16x32_bf16 v[108:111], v[124:127], v[172:175], v[108:111]
	v_mfma_f32_16x16x32_bf16 v[92:95], v[124:127], v[180:183], v[92:95]
	v_mfma_f32_16x16x32_bf16 v[88:91], v[140:143], v[180:183], v[88:91]
	v_mfma_f32_16x16x32_bf16 v[72:75], v[140:143], v[188:191], v[72:75]
	v_mfma_f32_16x16x32_bf16 v[76:79], v[124:127], v[188:191], v[76:79]
	s_setprio 0
	s_setprio 1
	v_mfma_f32_16x16x32_bf16 v[116:119], v[144:147], v[160:163], v[116:119]
	v_mfma_f32_16x16x32_bf16 v[112:115], v[152:155], v[160:163], v[112:115]
	v_mfma_f32_16x16x32_bf16 v[96:99], v[152:155], v[168:171], v[96:99]
	v_mfma_f32_16x16x32_bf16 v[100:103], v[144:147], v[168:171], v[100:103]
	v_mfma_f32_16x16x32_bf16 v[84:87], v[144:147], v[176:179], v[84:87]
	v_mfma_f32_16x16x32_bf16 v[80:83], v[152:155], v[176:179], v[80:83]
	v_mfma_f32_16x16x32_bf16 v[64:67], v[152:155], v[184:187], v[64:67]
	v_mfma_f32_16x16x32_bf16 v[68:71], v[144:147], v[184:187], v[68:71]
	v_mfma_f32_16x16x32_bf16 v[116:119], v[148:151], v[164:167], v[116:119]
	v_mfma_f32_16x16x32_bf16 v[112:115], v[156:159], v[164:167], v[112:115]
	v_mfma_f32_16x16x32_bf16 v[96:99], v[156:159], v[172:175], v[96:99]
	v_mfma_f32_16x16x32_bf16 v[100:103], v[148:151], v[172:175], v[100:103]
	v_mfma_f32_16x16x32_bf16 v[84:87], v[148:151], v[180:183], v[84:87]
	v_mfma_f32_16x16x32_bf16 v[80:83], v[156:159], v[180:183], v[80:83]
	v_mfma_f32_16x16x32_bf16 v[64:67], v[156:159], v[188:191], v[64:67]
	v_mfma_f32_16x16x32_bf16 v[68:71], v[148:151], v[188:191], v[68:71]
	s_setprio 0
	s_barrier
	s_add_i32 s42, s51, s17
	v_lshl_add_u64 v[208:209], s[0:1], 0, v[194:195]
	s_mov_b32 m0, s42
	ds_read_b128 v[160:163], v252 offset:16384
	ds_read_b128 v[164:167], v252 offset:17408
	ds_read_b128 v[168:171], v252 offset:18432
	ds_read_b128 v[172:175], v252 offset:19456
	ds_read_b128 v[176:179], v252 offset:20480
	ds_read_b128 v[180:183], v252 offset:21504
	ds_read_b128 v[184:187], v252 offset:22528
	ds_read_b128 v[188:191], v252 offset:23552
	global_load_lds_dwordx4 v[208:209], off
	s_add_i32 m0, s42, 0x2000
	s_add_u32 s42, s0, 0xc0000
	v_lshl_add_u64 v[210:211], s[0:1], 0, v[198:199]
	s_addc_u32 s43, s1, 0
	s_add_i32 s58, s52, s17
	global_load_lds_dwordx4 v[210:211], off
	v_lshl_add_u64 v[212:213], s[42:43], 0, v[194:195]
	s_mov_b32 m0, s58
	v_lshl_add_u64 v[214:215], s[46:47], 0, v[196:197]
	global_load_lds_dwordx4 v[212:213], off
	v_lshl_add_u64 v[212:213], s[42:43], 0, v[198:199]
	s_add_i32 m0, s58, 0x2000
	s_nop 0
	global_load_lds_dwordx4 v[212:213], off
	v_lshl_add_u64 v[212:213], s[46:47], 0, v[192:193]
	s_mov_b32 m0, s24
	s_nop 0
	global_load_lds_dwordx4 v[212:213], off
	s_mov_b32 m0, s25
	s_nop 0
	global_load_lds_dwordx4 v[214:215], off
	s_waitcnt vmcnt(8)
	s_waitcnt lgkmcnt(0)
	s_barrier
	s_setprio 1
	s_waitcnt lgkmcnt(0)
	v_mfma_f32_16x16x32_bf16 v[60:63], v[120:123], v[160:163], v[60:63]
	v_mfma_f32_16x16x32_bf16 v[56:59], v[136:139], v[160:163], v[56:59]
	v_mfma_f32_16x16x32_bf16 v[40:43], v[136:139], v[168:171], v[40:43]
	v_mfma_f32_16x16x32_bf16 v[44:47], v[120:123], v[168:171], v[44:47]
	v_mfma_f32_16x16x32_bf16 v[28:31], v[120:123], v[176:179], v[28:31]
	v_mfma_f32_16x16x32_bf16 v[24:27], v[136:139], v[176:179], v[24:27]
	v_mfma_f32_16x16x32_bf16 v[8:11], v[136:139], v[184:187], v[8:11]
	v_mfma_f32_16x16x32_bf16 v[12:15], v[120:123], v[184:187], v[12:15]
	v_mfma_f32_16x16x32_bf16 v[60:63], v[124:127], v[164:167], v[60:63]
	v_mfma_f32_16x16x32_bf16 v[56:59], v[140:143], v[164:167], v[56:59]
	v_mfma_f32_16x16x32_bf16 v[40:43], v[140:143], v[172:175], v[40:43]
	v_mfma_f32_16x16x32_bf16 v[44:47], v[124:127], v[172:175], v[44:47]
	v_mfma_f32_16x16x32_bf16 v[28:31], v[124:127], v[180:183], v[28:31]
	v_mfma_f32_16x16x32_bf16 v[24:27], v[140:143], v[180:183], v[24:27]
	v_mfma_f32_16x16x32_bf16 v[8:11], v[140:143], v[188:191], v[8:11]
	v_mfma_f32_16x16x32_bf16 v[12:15], v[124:127], v[188:191], v[12:15]
	s_setprio 0
	s_setprio 1
	v_mfma_f32_16x16x32_bf16 v[52:55], v[144:147], v[160:163], v[52:55]
	v_mfma_f32_16x16x32_bf16 v[48:51], v[152:155], v[160:163], v[48:51]
	v_mfma_f32_16x16x32_bf16 v[32:35], v[152:155], v[168:171], v[32:35]
	v_mfma_f32_16x16x32_bf16 v[36:39], v[144:147], v[168:171], v[36:39]
	v_mfma_f32_16x16x32_bf16 v[20:23], v[144:147], v[176:179], v[20:23]
	v_mfma_f32_16x16x32_bf16 v[16:19], v[152:155], v[176:179], v[16:19]
	v_mfma_f32_16x16x32_bf16 v[0:3], v[152:155], v[184:187], v[0:3]
	v_mfma_f32_16x16x32_bf16 v[4:7], v[144:147], v[184:187], v[4:7]
	v_mfma_f32_16x16x32_bf16 v[52:55], v[148:151], v[164:167], v[52:55]
	v_mfma_f32_16x16x32_bf16 v[48:51], v[156:159], v[164:167], v[48:51]
	v_mfma_f32_16x16x32_bf16 v[32:35], v[156:159], v[172:175], v[32:35]
	v_mfma_f32_16x16x32_bf16 v[36:39], v[148:151], v[172:175], v[36:39]
	v_mfma_f32_16x16x32_bf16 v[20:23], v[148:151], v[180:183], v[20:23]
	v_mfma_f32_16x16x32_bf16 v[16:19], v[156:159], v[180:183], v[16:19]
	v_mfma_f32_16x16x32_bf16 v[0:3], v[156:159], v[188:191], v[0:3]
	v_mfma_f32_16x16x32_bf16 v[4:7], v[148:151], v[188:191], v[4:7]
	s_setprio 0
	s_barrier
	s_add_i32 s58, 0, 0x18000
	s_add_i32 s59, 0, 0x1c000
	v_add_u32_e32 v140, s58, v248
	v_add_u32_e32 v156, s59, v248
	ds_read_b128 v[120:123], v140
	ds_read_b128 v[124:127], v140 offset:1024
	ds_read_b128 v[136:139], v140 offset:2048
	ds_read_b128 v[140:143], v140 offset:3072
	ds_read_b128 v[144:147], v156
	ds_read_b128 v[148:151], v156 offset:1024
	ds_read_b128 v[152:155], v156 offset:2048
	ds_read_b128 v[156:159], v156 offset:3072
	s_add_u32 s42, s46, 0xc0000
	s_addc_u32 s43, s47, 0
	s_mov_b32 m0, s26
	v_lshl_add_u64 v[216:217], s[42:43], 0, v[192:193]
	ds_read_b128 v[160:163], v252 offset:32768
	ds_read_b128 v[164:167], v252 offset:33792
	ds_read_b128 v[168:171], v252 offset:34816
	ds_read_b128 v[172:175], v252 offset:35840
	ds_read_b128 v[176:179], v252 offset:36864
	ds_read_b128 v[180:183], v252 offset:37888
	ds_read_b128 v[184:187], v252 offset:38912
	ds_read_b128 v[188:191], v252 offset:39936
	global_load_lds_dwordx4 v[216:217], off
	v_lshl_add_u64 v[216:217], s[42:43], 0, v[196:197]
	s_mov_b32 m0, s27
	s_nop 0
	global_load_lds_dwordx4 v[216:217], off
	s_waitcnt vmcnt(8)
	s_waitcnt lgkmcnt(0)
	s_barrier
	s_setprio 1
	s_waitcnt lgkmcnt(0)
	v_mfma_f32_16x16x32_bf16 v[132:135], v[120:123], v[160:163], v[132:135]
	v_mfma_f32_16x16x32_bf16 v[128:131], v[136:139], v[160:163], v[128:131]
	v_mfma_f32_16x16x32_bf16 v[104:107], v[136:139], v[168:171], v[104:107]
	v_mfma_f32_16x16x32_bf16 v[108:111], v[120:123], v[168:171], v[108:111]
	v_mfma_f32_16x16x32_bf16 v[92:95], v[120:123], v[176:179], v[92:95]
	v_mfma_f32_16x16x32_bf16 v[88:91], v[136:139], v[176:179], v[88:91]
	v_mfma_f32_16x16x32_bf16 v[72:75], v[136:139], v[184:187], v[72:75]
	v_mfma_f32_16x16x32_bf16 v[76:79], v[120:123], v[184:187], v[76:79]
	v_mfma_f32_16x16x32_bf16 v[132:135], v[124:127], v[164:167], v[132:135]
	v_mfma_f32_16x16x32_bf16 v[128:131], v[140:143], v[164:167], v[128:131]
	v_mfma_f32_16x16x32_bf16 v[104:107], v[140:143], v[172:175], v[104:107]
	v_mfma_f32_16x16x32_bf16 v[108:111], v[124:127], v[172:175], v[108:111]
	v_mfma_f32_16x16x32_bf16 v[92:95], v[124:127], v[180:183], v[92:95]
	v_mfma_f32_16x16x32_bf16 v[88:91], v[140:143], v[180:183], v[88:91]
	v_mfma_f32_16x16x32_bf16 v[72:75], v[140:143], v[188:191], v[72:75]
	v_mfma_f32_16x16x32_bf16 v[76:79], v[124:127], v[188:191], v[76:79]
	s_setprio 0
	s_setprio 1
	v_mfma_f32_16x16x32_bf16 v[116:119], v[144:147], v[160:163], v[116:119]
	v_mfma_f32_16x16x32_bf16 v[112:115], v[152:155], v[160:163], v[112:115]
	v_mfma_f32_16x16x32_bf16 v[96:99], v[152:155], v[168:171], v[96:99]
	v_mfma_f32_16x16x32_bf16 v[100:103], v[144:147], v[168:171], v[100:103]
	v_mfma_f32_16x16x32_bf16 v[84:87], v[144:147], v[176:179], v[84:87]
	v_mfma_f32_16x16x32_bf16 v[80:83], v[152:155], v[176:179], v[80:83]
	v_mfma_f32_16x16x32_bf16 v[64:67], v[152:155], v[184:187], v[64:67]
	v_mfma_f32_16x16x32_bf16 v[68:71], v[144:147], v[184:187], v[68:71]
	v_mfma_f32_16x16x32_bf16 v[116:119], v[148:151], v[164:167], v[116:119]
	v_mfma_f32_16x16x32_bf16 v[112:115], v[156:159], v[164:167], v[112:115]
	v_mfma_f32_16x16x32_bf16 v[96:99], v[156:159], v[172:175], v[96:99]
	v_mfma_f32_16x16x32_bf16 v[100:103], v[148:151], v[172:175], v[100:103]
	v_mfma_f32_16x16x32_bf16 v[84:87], v[148:151], v[180:183], v[84:87]
	v_mfma_f32_16x16x32_bf16 v[80:83], v[156:159], v[180:183], v[80:83]
	v_mfma_f32_16x16x32_bf16 v[64:67], v[156:159], v[188:191], v[64:67]
	v_mfma_f32_16x16x32_bf16 v[68:71], v[148:151], v[188:191], v[68:71]
	s_setprio 0
	s_barrier
	s_add_i32 s42, s58, s17
	v_lshl_add_u64 v[208:209], v[208:209], 0, s[36:37]
	s_mov_b32 m0, s42
	ds_read_b128 v[160:163], v252 offset:49152
	ds_read_b128 v[164:167], v252 offset:50176
	ds_read_b128 v[168:171], v252 offset:51200
	ds_read_b128 v[172:175], v252 offset:52224
	ds_read_b128 v[176:179], v252 offset:53248
	ds_read_b128 v[180:183], v252 offset:54272
	ds_read_b128 v[184:187], v252 offset:55296
	ds_read_b128 v[188:191], v252 offset:56320
	global_load_lds_dwordx4 v[208:209], off
	s_add_i32 m0, s42, 0x2000
	s_add_u32 s0, s0, 0xc0080
	v_lshl_add_u64 v[208:209], v[210:211], 0, s[36:37]
	s_addc_u32 s1, s1, 0
	s_add_i32 s42, s59, s17
	global_load_lds_dwordx4 v[208:209], off
	v_lshl_add_u64 v[208:209], s[0:1], 0, v[194:195]
	s_mov_b32 m0, s42
	s_nop 0
	global_load_lds_dwordx4 v[208:209], off
	v_lshl_add_u64 v[208:209], s[0:1], 0, v[198:199]
	s_add_i32 m0, s42, 0x2000
	s_nop 0
	global_load_lds_dwordx4 v[208:209], off
	v_lshl_add_u64 v[208:209], v[212:213], 0, s[36:37]
	s_mov_b32 m0, s31
	s_nop 0
	global_load_lds_dwordx4 v[208:209], off
	v_lshl_add_u64 v[208:209], v[214:215], 0, s[36:37]
	s_mov_b32 m0, s33
	s_nop 0
	global_load_lds_dwordx4 v[208:209], off
	s_waitcnt vmcnt(8)
	s_waitcnt lgkmcnt(0)
	s_barrier
	s_setprio 1
	s_waitcnt lgkmcnt(0)
	v_mfma_f32_16x16x32_bf16 v[60:63], v[120:123], v[160:163], v[60:63]
	v_mfma_f32_16x16x32_bf16 v[56:59], v[136:139], v[160:163], v[56:59]
	v_mfma_f32_16x16x32_bf16 v[40:43], v[136:139], v[168:171], v[40:43]
	v_mfma_f32_16x16x32_bf16 v[44:47], v[120:123], v[168:171], v[44:47]
	v_mfma_f32_16x16x32_bf16 v[28:31], v[120:123], v[176:179], v[28:31]
	v_mfma_f32_16x16x32_bf16 v[24:27], v[136:139], v[176:179], v[24:27]
	v_mfma_f32_16x16x32_bf16 v[8:11], v[136:139], v[184:187], v[8:11]
	v_mfma_f32_16x16x32_bf16 v[12:15], v[120:123], v[184:187], v[12:15]
	v_mfma_f32_16x16x32_bf16 v[60:63], v[124:127], v[164:167], v[60:63]
	v_mfma_f32_16x16x32_bf16 v[56:59], v[140:143], v[164:167], v[56:59]
	v_mfma_f32_16x16x32_bf16 v[40:43], v[140:143], v[172:175], v[40:43]
	v_mfma_f32_16x16x32_bf16 v[44:47], v[124:127], v[172:175], v[44:47]
	v_mfma_f32_16x16x32_bf16 v[28:31], v[124:127], v[180:183], v[28:31]
	v_mfma_f32_16x16x32_bf16 v[24:27], v[140:143], v[180:183], v[24:27]
	v_mfma_f32_16x16x32_bf16 v[8:11], v[140:143], v[188:191], v[8:11]
	v_mfma_f32_16x16x32_bf16 v[12:15], v[124:127], v[188:191], v[12:15]
	s_setprio 0
	s_setprio 1
	v_mfma_f32_16x16x32_bf16 v[52:55], v[144:147], v[160:163], v[52:55]
	v_mfma_f32_16x16x32_bf16 v[48:51], v[152:155], v[160:163], v[48:51]
	v_mfma_f32_16x16x32_bf16 v[32:35], v[152:155], v[168:171], v[32:35]
	v_mfma_f32_16x16x32_bf16 v[36:39], v[144:147], v[168:171], v[36:39]
	v_mfma_f32_16x16x32_bf16 v[20:23], v[144:147], v[176:179], v[20:23]
	v_mfma_f32_16x16x32_bf16 v[16:19], v[152:155], v[176:179], v[16:19]
	v_mfma_f32_16x16x32_bf16 v[0:3], v[152:155], v[184:187], v[0:3]
	v_mfma_f32_16x16x32_bf16 v[4:7], v[144:147], v[184:187], v[4:7]
	v_mfma_f32_16x16x32_bf16 v[52:55], v[148:151], v[164:167], v[52:55]
	v_mfma_f32_16x16x32_bf16 v[48:51], v[156:159], v[164:167], v[48:51]
	v_mfma_f32_16x16x32_bf16 v[32:35], v[156:159], v[172:175], v[32:35]
	v_mfma_f32_16x16x32_bf16 v[36:39], v[148:151], v[172:175], v[36:39]
	v_mfma_f32_16x16x32_bf16 v[20:23], v[148:151], v[180:183], v[20:23]
	v_mfma_f32_16x16x32_bf16 v[16:19], v[156:159], v[180:183], v[16:19]
	v_mfma_f32_16x16x32_bf16 v[0:3], v[156:159], v[188:191], v[0:3]
	v_mfma_f32_16x16x32_bf16 v[4:7], v[148:151], v[188:191], v[4:7]
	s_setprio 0
	s_barrier
	s_add_i32 s57, s57, 2
	s_add_u32 s55, s55, 0x100
	s_addc_u32 s56, s56, 0
	s_cmp_gt_u32 s57, 45
	s_mov_b64 s[42:43], s[44:45]
	s_cbranch_scc0 .LBB0_851
	s_and_b64 vcc, exec, s[38:39]
	s_cbranch_vccz .LBB0_854
	s_barrier

.LBB0_899:
	ds_read_b128 v[128:131], v223
	ds_read_b128 v[132:135], v223 offset:1024
	ds_read_b128 v[136:139], v223 offset:2048
	ds_read_b128 v[140:143], v223 offset:3072
	ds_read_b128 v[144:147], v224
	ds_read_b128 v[148:151], v224 offset:1024
	ds_read_b128 v[152:155], v224 offset:2048
	ds_read_b128 v[156:159], v224 offset:3072
	s_add_u32 s46, s44, 0x100
	s_addc_u32 s47, s45, 0
	s_cmp_eq_u32 s58, 44
	s_cselect_b32 s49, s9, s47
	s_cselect_b32 s48, s8, s46
	s_cselect_b32 s1, s43, s57
	s_cselect_b32 s0, s42, s56
	v_lshl_add_u64 v[208:209], s[44:45], 0, v[192:193]
	s_add_i32 m0, s26, 0xc000
	ds_read_b128 v[160:163], v225
	ds_read_b128 v[164:167], v225 offset:1024
	ds_read_b128 v[168:171], v225 offset:2048
	ds_read_b128 v[172:175], v225 offset:3072
	ds_read_b128 v[176:179], v225 offset:4096
	ds_read_b128 v[180:183], v225 offset:5120
	ds_read_b128 v[200:203], v225 offset:6144
	ds_read_b128 v[204:207], v225 offset:7168
	global_load_lds_dwordx4 v[208:209], off
	v_lshl_add_u64 v[208:209], s[44:45], 0, v[194:195]
	s_add_i32 m0, s26, 0xe000
	s_nop 0
	global_load_lds_dwordx4 v[208:209], off
	s_waitcnt vmcnt(8)
	s_waitcnt lgkmcnt(0)
	s_barrier
	s_setprio 1
	s_waitcnt lgkmcnt(0)
	v_mfma_f32_16x16x32_bf16 v[124:127], v[128:131], v[160:163], v[124:127]
	v_mfma_f32_16x16x32_bf16 v[120:123], v[136:139], v[160:163], v[120:123]
	v_mfma_f32_16x16x32_bf16 v[104:107], v[136:139], v[168:171], v[104:107]
	v_mfma_f32_16x16x32_bf16 v[108:111], v[128:131], v[168:171], v[108:111]
	v_mfma_f32_16x16x32_bf16 v[92:95], v[128:131], v[176:179], v[92:95]
	v_mfma_f32_16x16x32_bf16 v[88:91], v[136:139], v[176:179], v[88:91]
	v_mfma_f32_16x16x32_bf16 v[72:75], v[136:139], v[200:203], v[72:75]
	v_mfma_f32_16x16x32_bf16 v[76:79], v[128:131], v[200:203], v[76:79]
	v_mfma_f32_16x16x32_bf16 v[124:127], v[132:135], v[164:167], v[124:127]
	v_mfma_f32_16x16x32_bf16 v[120:123], v[140:143], v[164:167], v[120:123]
	v_mfma_f32_16x16x32_bf16 v[104:107], v[140:143], v[172:175], v[104:107]
	v_mfma_f32_16x16x32_bf16 v[108:111], v[132:135], v[172:175], v[108:111]
	v_mfma_f32_16x16x32_bf16 v[92:95], v[132:135], v[180:183], v[92:95]
	v_mfma_f32_16x16x32_bf16 v[88:91], v[140:143], v[180:183], v[88:91]
	v_mfma_f32_16x16x32_bf16 v[72:75], v[140:143], v[204:207], v[72:75]
	v_mfma_f32_16x16x32_bf16 v[76:79], v[132:135], v[204:207], v[76:79]
	s_setprio 0
	s_setprio 1
	v_mfma_f32_16x16x32_bf16 v[116:119], v[144:147], v[160:163], v[116:119]
	v_mfma_f32_16x16x32_bf16 v[112:115], v[152:155], v[160:163], v[112:115]
	v_mfma_f32_16x16x32_bf16 v[96:99], v[152:155], v[168:171], v[96:99]
	v_mfma_f32_16x16x32_bf16 v[100:103], v[144:147], v[168:171], v[100:103]
	v_mfma_f32_16x16x32_bf16 v[84:87], v[144:147], v[176:179], v[84:87]
	v_mfma_f32_16x16x32_bf16 v[80:83], v[152:155], v[176:179], v[80:83]
	v_mfma_f32_16x16x32_bf16 v[64:67], v[152:155], v[200:203], v[64:67]
	v_mfma_f32_16x16x32_bf16 v[68:71], v[144:147], v[200:203], v[68:71]
	v_mfma_f32_16x16x32_bf16 v[116:119], v[148:151], v[164:167], v[116:119]
	v_mfma_f32_16x16x32_bf16 v[112:115], v[156:159], v[164:167], v[112:115]
	v_mfma_f32_16x16x32_bf16 v[96:99], v[156:159], v[172:175], v[96:99]
	v_mfma_f32_16x16x32_bf16 v[100:103], v[148:151], v[172:175], v[100:103]
	v_mfma_f32_16x16x32_bf16 v[84:87], v[148:151], v[180:183], v[84:87]
	v_mfma_f32_16x16x32_bf16 v[80:83], v[156:159], v[180:183], v[80:83]
	v_mfma_f32_16x16x32_bf16 v[64:67], v[156:159], v[204:207], v[64:67]
	v_mfma_f32_16x16x32_bf16 v[68:71], v[148:151], v[204:207], v[68:71]
	s_setprio 0
	s_barrier
	s_add_i32 s44, s54, s17
	v_lshl_add_u64 v[208:209], s[0:1], 0, v[186:187]
	s_mov_b32 m0, s44
	ds_read_b128 v[160:163], v225 offset:16384
	ds_read_b128 v[164:167], v225 offset:17408
	ds_read_b128 v[168:171], v225 offset:18432
	ds_read_b128 v[172:175], v225 offset:19456
	ds_read_b128 v[176:179], v225 offset:20480
	ds_read_b128 v[180:183], v225 offset:21504
	ds_read_b128 v[200:203], v225 offset:22528
	ds_read_b128 v[204:207], v225 offset:23552
	global_load_lds_dwordx4 v[208:209], off
	s_add_i32 m0, s44, 0x2000
	s_add_u32 s44, s0, 0xc0000
	v_lshl_add_u64 v[210:211], s[0:1], 0, v[190:191]
	s_addc_u32 s45, s1, 0
	s_add_i32 s59, s55, s17
	global_load_lds_dwordx4 v[210:211], off
	v_lshl_add_u64 v[212:213], s[44:45], 0, v[186:187]
	s_mov_b32 m0, s59
	v_lshl_add_u64 v[214:215], s[48:49], 0, v[188:189]
	global_load_lds_dwordx4 v[212:213], off
	v_lshl_add_u64 v[212:213], s[44:45], 0, v[190:191]
	s_add_i32 m0, s59, 0x2000
	s_nop 0
	global_load_lds_dwordx4 v[212:213], off
	v_lshl_add_u64 v[212:213], s[48:49], 0, v[184:185]
	s_mov_b32 m0, s26
	s_nop 0
	global_load_lds_dwordx4 v[212:213], off
	s_mov_b32 m0, s27
	s_nop 0
	global_load_lds_dwordx4 v[214:215], off
	s_waitcnt vmcnt(8)
	s_waitcnt lgkmcnt(0)
	s_barrier
	s_setprio 1
	s_waitcnt lgkmcnt(0)
	v_mfma_f32_16x16x32_bf16 v[60:63], v[128:131], v[160:163], v[60:63]
	v_mfma_f32_16x16x32_bf16 v[56:59], v[136:139], v[160:163], v[56:59]
	v_mfma_f32_16x16x32_bf16 v[40:43], v[136:139], v[168:171], v[40:43]
	v_mfma_f32_16x16x32_bf16 v[44:47], v[128:131], v[168:171], v[44:47]
	v_mfma_f32_16x16x32_bf16 v[28:31], v[128:131], v[176:179], v[28:31]
	v_mfma_f32_16x16x32_bf16 v[24:27], v[136:139], v[176:179], v[24:27]
	v_mfma_f32_16x16x32_bf16 v[8:11], v[136:139], v[200:203], v[8:11]
	v_mfma_f32_16x16x32_bf16 v[12:15], v[128:131], v[200:203], v[12:15]
	v_mfma_f32_16x16x32_bf16 v[60:63], v[132:135], v[164:167], v[60:63]
	v_mfma_f32_16x16x32_bf16 v[56:59], v[140:143], v[164:167], v[56:59]
	v_mfma_f32_16x16x32_bf16 v[40:43], v[140:143], v[172:175], v[40:43]
	v_mfma_f32_16x16x32_bf16 v[44:47], v[132:135], v[172:175], v[44:47]
	v_mfma_f32_16x16x32_bf16 v[28:31], v[132:135], v[180:183], v[28:31]
	v_mfma_f32_16x16x32_bf16 v[24:27], v[140:143], v[180:183], v[24:27]
	v_mfma_f32_16x16x32_bf16 v[8:11], v[140:143], v[204:207], v[8:11]
	v_mfma_f32_16x16x32_bf16 v[12:15], v[132:135], v[204:207], v[12:15]
	s_setprio 0
	s_setprio 1
	v_mfma_f32_16x16x32_bf16 v[52:55], v[144:147], v[160:163], v[52:55]
	v_mfma_f32_16x16x32_bf16 v[48:51], v[152:155], v[160:163], v[48:51]
	v_mfma_f32_16x16x32_bf16 v[32:35], v[152:155], v[168:171], v[32:35]
	v_mfma_f32_16x16x32_bf16 v[36:39], v[144:147], v[168:171], v[36:39]
	v_mfma_f32_16x16x32_bf16 v[20:23], v[144:147], v[176:179], v[20:23]
	v_mfma_f32_16x16x32_bf16 v[16:19], v[152:155], v[176:179], v[16:19]
	v_mfma_f32_16x16x32_bf16 v[0:3], v[152:155], v[200:203], v[0:3]
	v_mfma_f32_16x16x32_bf16 v[4:7], v[144:147], v[200:203], v[4:7]
	v_mfma_f32_16x16x32_bf16 v[52:55], v[148:151], v[164:167], v[52:55]
	v_mfma_f32_16x16x32_bf16 v[48:51], v[156:159], v[164:167], v[48:51]
	v_mfma_f32_16x16x32_bf16 v[32:35], v[156:159], v[172:175], v[32:35]
	v_mfma_f32_16x16x32_bf16 v[36:39], v[148:151], v[172:175], v[36:39]
	v_mfma_f32_16x16x32_bf16 v[20:23], v[148:151], v[180:183], v[20:23]
	v_mfma_f32_16x16x32_bf16 v[16:19], v[156:159], v[180:183], v[16:19]
	v_mfma_f32_16x16x32_bf16 v[0:3], v[156:159], v[204:207], v[0:3]
	v_mfma_f32_16x16x32_bf16 v[4:7], v[148:151], v[204:207], v[4:7]
	s_setprio 0
	s_barrier
	s_add_i32 s59, 0, 0x18000
	s_add_i32 s60, 0, 0x1c000
	v_add_u32_e32 v140, s59, v221
	v_add_u32_e32 v156, s60, v221
	ds_read_b128 v[128:131], v140
	ds_read_b128 v[132:135], v140 offset:1024
	ds_read_b128 v[136:139], v140 offset:2048
	ds_read_b128 v[140:143], v140 offset:3072
	ds_read_b128 v[144:147], v156
	ds_read_b128 v[148:151], v156 offset:1024
	ds_read_b128 v[152:155], v156 offset:2048
	ds_read_b128 v[156:159], v156 offset:3072
	s_add_u32 s44, s48, 0xc0000
	s_addc_u32 s45, s49, 0
	s_mov_b32 m0, s30
	v_lshl_add_u64 v[216:217], s[44:45], 0, v[184:185]
	ds_read_b128 v[160:163], v225 offset:32768
	ds_read_b128 v[164:167], v225 offset:33792
	ds_read_b128 v[168:171], v225 offset:34816
	ds_read_b128 v[172:175], v225 offset:35840
	ds_read_b128 v[176:179], v225 offset:36864
	ds_read_b128 v[180:183], v225 offset:37888
	ds_read_b128 v[200:203], v225 offset:38912
	ds_read_b128 v[204:207], v225 offset:39936
	global_load_lds_dwordx4 v[216:217], off
	v_lshl_add_u64 v[216:217], s[44:45], 0, v[188:189]
	s_mov_b32 m0, s31
	s_nop 0
	global_load_lds_dwordx4 v[216:217], off
	s_waitcnt vmcnt(8)
	s_waitcnt lgkmcnt(0)
	s_barrier
	s_setprio 1
	s_waitcnt lgkmcnt(0)
	v_mfma_f32_16x16x32_bf16 v[124:127], v[128:131], v[160:163], v[124:127]
	v_mfma_f32_16x16x32_bf16 v[120:123], v[136:139], v[160:163], v[120:123]
	v_mfma_f32_16x16x32_bf16 v[104:107], v[136:139], v[168:171], v[104:107]
	v_mfma_f32_16x16x32_bf16 v[108:111], v[128:131], v[168:171], v[108:111]
	v_mfma_f32_16x16x32_bf16 v[92:95], v[128:131], v[176:179], v[92:95]
	v_mfma_f32_16x16x32_bf16 v[88:91], v[136:139], v[176:179], v[88:91]
	v_mfma_f32_16x16x32_bf16 v[72:75], v[136:139], v[200:203], v[72:75]
	v_mfma_f32_16x16x32_bf16 v[76:79], v[128:131], v[200:203], v[76:79]
	v_mfma_f32_16x16x32_bf16 v[124:127], v[132:135], v[164:167], v[124:127]
	v_mfma_f32_16x16x32_bf16 v[120:123], v[140:143], v[164:167], v[120:123]
	v_mfma_f32_16x16x32_bf16 v[104:107], v[140:143], v[172:175], v[104:107]
	v_mfma_f32_16x16x32_bf16 v[108:111], v[132:135], v[172:175], v[108:111]
	v_mfma_f32_16x16x32_bf16 v[92:95], v[132:135], v[180:183], v[92:95]
	v_mfma_f32_16x16x32_bf16 v[88:91], v[140:143], v[180:183], v[88:91]
	v_mfma_f32_16x16x32_bf16 v[72:75], v[140:143], v[204:207], v[72:75]
	v_mfma_f32_16x16x32_bf16 v[76:79], v[132:135], v[204:207], v[76:79]
	s_setprio 0
	s_setprio 1
	v_mfma_f32_16x16x32_bf16 v[116:119], v[144:147], v[160:163], v[116:119]
	v_mfma_f32_16x16x32_bf16 v[112:115], v[152:155], v[160:163], v[112:115]
	v_mfma_f32_16x16x32_bf16 v[96:99], v[152:155], v[168:171], v[96:99]
	v_mfma_f32_16x16x32_bf16 v[100:103], v[144:147], v[168:171], v[100:103]
	v_mfma_f32_16x16x32_bf16 v[84:87], v[144:147], v[176:179], v[84:87]
	v_mfma_f32_16x16x32_bf16 v[80:83], v[152:155], v[176:179], v[80:83]
	v_mfma_f32_16x16x32_bf16 v[64:67], v[152:155], v[200:203], v[64:67]
	v_mfma_f32_16x16x32_bf16 v[68:71], v[144:147], v[200:203], v[68:71]
	v_mfma_f32_16x16x32_bf16 v[116:119], v[148:151], v[164:167], v[116:119]
	v_mfma_f32_16x16x32_bf16 v[112:115], v[156:159], v[164:167], v[112:115]
	v_mfma_f32_16x16x32_bf16 v[96:99], v[156:159], v[172:175], v[96:99]
	v_mfma_f32_16x16x32_bf16 v[100:103], v[148:151], v[172:175], v[100:103]
	v_mfma_f32_16x16x32_bf16 v[84:87], v[148:151], v[180:183], v[84:87]
	v_mfma_f32_16x16x32_bf16 v[80:83], v[156:159], v[180:183], v[80:83]
	v_mfma_f32_16x16x32_bf16 v[64:67], v[156:159], v[204:207], v[64:67]
	v_mfma_f32_16x16x32_bf16 v[68:71], v[148:151], v[204:207], v[68:71]
	s_setprio 0
	s_barrier
	s_add_i32 s44, s59, s17
	v_lshl_add_u64 v[208:209], v[208:209], 0, s[38:39]
	s_mov_b32 m0, s44
	ds_read_b128 v[160:163], v225 offset:49152
	ds_read_b128 v[164:167], v225 offset:50176
	ds_read_b128 v[168:171], v225 offset:51200
	ds_read_b128 v[172:175], v225 offset:52224
	ds_read_b128 v[176:179], v225 offset:53248
	ds_read_b128 v[180:183], v225 offset:54272
	ds_read_b128 v[200:203], v225 offset:55296
	ds_read_b128 v[204:207], v225 offset:56320
	global_load_lds_dwordx4 v[208:209], off
	s_add_i32 m0, s44, 0x2000
	s_add_u32 s0, s0, 0xc0080
	v_lshl_add_u64 v[208:209], v[210:211], 0, s[38:39]
	s_addc_u32 s1, s1, 0
	s_add_i32 s44, s60, s17
	global_load_lds_dwordx4 v[208:209], off
	v_lshl_add_u64 v[208:209], s[0:1], 0, v[186:187]
	s_mov_b32 m0, s44
	s_nop 0
	global_load_lds_dwordx4 v[208:209], off
	v_lshl_add_u64 v[208:209], s[0:1], 0, v[190:191]
	s_add_i32 m0, s44, 0x2000
	s_nop 0
	global_load_lds_dwordx4 v[208:209], off
	v_lshl_add_u64 v[208:209], v[212:213], 0, s[38:39]
	s_mov_b32 m0, s51
	s_nop 0
	global_load_lds_dwordx4 v[208:209], off
	v_lshl_add_u64 v[208:209], v[214:215], 0, s[38:39]
	s_mov_b32 m0, s52
	s_nop 0
	global_load_lds_dwordx4 v[208:209], off
	s_waitcnt vmcnt(8)
	s_waitcnt lgkmcnt(0)
	s_barrier
	s_setprio 1
	s_waitcnt lgkmcnt(0)
	v_mfma_f32_16x16x32_bf16 v[60:63], v[128:131], v[160:163], v[60:63]
	v_mfma_f32_16x16x32_bf16 v[56:59], v[136:139], v[160:163], v[56:59]
	v_mfma_f32_16x16x32_bf16 v[40:43], v[136:139], v[168:171], v[40:43]
	v_mfma_f32_16x16x32_bf16 v[44:47], v[128:131], v[168:171], v[44:47]
	v_mfma_f32_16x16x32_bf16 v[28:31], v[128:131], v[176:179], v[28:31]
	v_mfma_f32_16x16x32_bf16 v[24:27], v[136:139], v[176:179], v[24:27]
	v_mfma_f32_16x16x32_bf16 v[8:11], v[136:139], v[200:203], v[8:11]
	v_mfma_f32_16x16x32_bf16 v[12:15], v[128:131], v[200:203], v[12:15]
	v_mfma_f32_16x16x32_bf16 v[60:63], v[132:135], v[164:167], v[60:63]
	v_mfma_f32_16x16x32_bf16 v[56:59], v[140:143], v[164:167], v[56:59]
	v_mfma_f32_16x16x32_bf16 v[40:43], v[140:143], v[172:175], v[40:43]
	v_mfma_f32_16x16x32_bf16 v[44:47], v[132:135], v[172:175], v[44:47]
	v_mfma_f32_16x16x32_bf16 v[28:31], v[132:135], v[180:183], v[28:31]
	v_mfma_f32_16x16x32_bf16 v[24:27], v[140:143], v[180:183], v[24:27]
	v_mfma_f32_16x16x32_bf16 v[8:11], v[140:143], v[204:207], v[8:11]
	v_mfma_f32_16x16x32_bf16 v[12:15], v[132:135], v[204:207], v[12:15]
	s_setprio 0
	s_setprio 1
	v_mfma_f32_16x16x32_bf16 v[52:55], v[144:147], v[160:163], v[52:55]
	v_mfma_f32_16x16x32_bf16 v[48:51], v[152:155], v[160:163], v[48:51]
	v_mfma_f32_16x16x32_bf16 v[32:35], v[152:155], v[168:171], v[32:35]
	v_mfma_f32_16x16x32_bf16 v[36:39], v[144:147], v[168:171], v[36:39]
	v_mfma_f32_16x16x32_bf16 v[20:23], v[144:147], v[176:179], v[20:23]
	v_mfma_f32_16x16x32_bf16 v[16:19], v[152:155], v[176:179], v[16:19]
	v_mfma_f32_16x16x32_bf16 v[0:3], v[152:155], v[200:203], v[0:3]
	v_mfma_f32_16x16x32_bf16 v[4:7], v[144:147], v[200:203], v[4:7]
	v_mfma_f32_16x16x32_bf16 v[52:55], v[148:151], v[164:167], v[52:55]
	v_mfma_f32_16x16x32_bf16 v[48:51], v[156:159], v[164:167], v[48:51]
	v_mfma_f32_16x16x32_bf16 v[32:35], v[156:159], v[172:175], v[32:35]
	v_mfma_f32_16x16x32_bf16 v[36:39], v[148:151], v[172:175], v[36:39]
	v_mfma_f32_16x16x32_bf16 v[20:23], v[148:151], v[180:183], v[20:23]
	v_mfma_f32_16x16x32_bf16 v[16:19], v[156:159], v[180:183], v[16:19]
	v_mfma_f32_16x16x32_bf16 v[0:3], v[156:159], v[204:207], v[0:3]
	v_mfma_f32_16x16x32_bf16 v[4:7], v[148:151], v[204:207], v[4:7]
	s_setprio 0
	s_barrier
	s_add_i32 s58, s58, 2
	s_add_u32 s56, s56, 0x100
	s_addc_u32 s57, s57, 0
	s_cmp_gt_u32 s58, 45
	s_mov_b64 s[44:45], s[46:47]
	s_cbranch_scc0 .LBB0_899
	s_and_b64 vcc, exec, s[40:41]
	s_cbranch_vccz .LBB0_902
	s_barrier
